# v55: v41 with every 16-MFMA run of the 7 GEMM K-loops 8-byte aligned (no MFMA encoding straddles a 64-B line) by deleting the repeated lgkmcnt(0) wait ahead of misaligned run pairs
# baseline (speedup 1.0000x reference)
.LBB0_374:
	ds_read_b128 v[152:155], v157
	ds_read_b128 v[160:163], v157 offset:1024
	ds_read_b128 v[164:167], v157 offset:2048
	ds_read_b128 v[168:171], v157 offset:3072
	ds_read_b128 v[172:175], v158
	ds_read_b128 v[176:179], v158 offset:1024
	ds_read_b128 v[180:183], v158 offset:2048
	ds_read_b128 v[184:187], v158 offset:3072
	s_add_u32 s28, s26, 0xfffc0080
	s_addc_u32 s29, s27, -1
	s_cmp_eq_u32 s80, 12
	s_cselect_b32 s31, s7, s29
	s_cselect_b32 s30, s21, s28
	s_cselect_b32 s29, s19, s59
	s_cselect_b32 s28, s57, s58
	v_lshl_add_u64 v[222:223], s[26:27], 0, v[144:145]
	s_add_i32 m0, s9, 0xc000
	ds_read_b128 v[188:191], v159
	ds_read_b128 v[192:195], v159 offset:1024
	ds_read_b128 v[196:199], v159 offset:2048
	ds_read_b128 v[200:203], v159 offset:3072
	ds_read_b128 v[204:207], v159 offset:4096
	ds_read_b128 v[210:213], v159 offset:5120
	ds_read_b128 v[214:217], v159 offset:6144
	ds_read_b128 v[218:221], v159 offset:7168
	global_load_lds_dwordx4 v[222:223], off
	v_lshl_add_u64 v[222:223], s[26:27], 0, v[146:147]
	s_add_i32 m0, s9, 0xe000
	s_nop 0
	global_load_lds_dwordx4 v[222:223], off
	s_waitcnt vmcnt(8)
	s_waitcnt lgkmcnt(0)
	s_barrier
	s_setprio 1
	v_mfma_f32_16x16x32_bf16 v[126:129], v[152:155], v[188:191], v[126:129]
	v_mfma_f32_16x16x32_bf16 v[122:125], v[164:167], v[188:191], v[122:125]
	v_mfma_f32_16x16x32_bf16 v[110:113], v[152:155], v[196:199], v[110:113]
	v_mfma_f32_16x16x32_bf16 v[106:109], v[164:167], v[196:199], v[106:109]
	v_mfma_f32_16x16x32_bf16 v[94:97], v[152:155], v[204:207], v[94:97]
	v_mfma_f32_16x16x32_bf16 v[90:93], v[164:167], v[204:207], v[90:93]
	v_mfma_f32_16x16x32_bf16 v[78:81], v[152:155], v[214:217], v[78:81]
	v_mfma_f32_16x16x32_bf16 v[74:77], v[164:167], v[214:217], v[74:77]
	v_mfma_f32_16x16x32_bf16 v[126:129], v[160:163], v[192:195], v[126:129]
	v_mfma_f32_16x16x32_bf16 v[122:125], v[168:171], v[192:195], v[122:125]
	v_mfma_f32_16x16x32_bf16 v[110:113], v[160:163], v[200:203], v[110:113]
	v_mfma_f32_16x16x32_bf16 v[106:109], v[168:171], v[200:203], v[106:109]
	v_mfma_f32_16x16x32_bf16 v[94:97], v[160:163], v[210:213], v[94:97]
	v_mfma_f32_16x16x32_bf16 v[90:93], v[168:171], v[210:213], v[90:93]
	v_mfma_f32_16x16x32_bf16 v[78:81], v[160:163], v[218:221], v[78:81]
	v_mfma_f32_16x16x32_bf16 v[74:77], v[168:171], v[218:221], v[74:77]
	s_setprio 0
	s_setprio 1
	v_mfma_f32_16x16x32_bf16 v[118:121], v[172:175], v[188:191], v[118:121]
	v_mfma_f32_16x16x32_bf16 v[114:117], v[180:183], v[188:191], v[114:117]
	v_mfma_f32_16x16x32_bf16 v[102:105], v[172:175], v[196:199], v[102:105]
	v_mfma_f32_16x16x32_bf16 v[98:101], v[180:183], v[196:199], v[98:101]
	v_mfma_f32_16x16x32_bf16 v[86:89], v[172:175], v[204:207], v[86:89]
	v_mfma_f32_16x16x32_bf16 v[82:85], v[180:183], v[204:207], v[82:85]
	v_mfma_f32_16x16x32_bf16 v[70:73], v[172:175], v[214:217], v[70:73]
	v_mfma_f32_16x16x32_bf16 v[66:69], v[180:183], v[214:217], v[66:69]
	v_mfma_f32_16x16x32_bf16 v[118:121], v[176:179], v[192:195], v[118:121]
	v_mfma_f32_16x16x32_bf16 v[114:117], v[184:187], v[192:195], v[114:117]
	v_mfma_f32_16x16x32_bf16 v[102:105], v[176:179], v[200:203], v[102:105]
	v_mfma_f32_16x16x32_bf16 v[98:101], v[184:187], v[200:203], v[98:101]
	v_mfma_f32_16x16x32_bf16 v[86:89], v[176:179], v[210:213], v[86:89]
	v_mfma_f32_16x16x32_bf16 v[82:85], v[184:187], v[210:213], v[82:85]
	v_mfma_f32_16x16x32_bf16 v[70:73], v[176:179], v[218:221], v[70:73]
	v_mfma_f32_16x16x32_bf16 v[66:69], v[184:187], v[218:221], v[66:69]
	s_setprio 0
	s_barrier
	s_add_i32 s81, s44, s35
	v_lshl_add_u64 v[222:223], s[28:29], 0, v[132:133]
	s_mov_b32 m0, s81
	ds_read_b128 v[188:191], v159 offset:16384
	ds_read_b128 v[192:195], v159 offset:17408
	ds_read_b128 v[196:199], v159 offset:18432
	ds_read_b128 v[200:203], v159 offset:19456
	ds_read_b128 v[204:207], v159 offset:20480
	ds_read_b128 v[210:213], v159 offset:21504
	ds_read_b128 v[214:217], v159 offset:22528
	ds_read_b128 v[218:221], v159 offset:23552
	global_load_lds_dwordx4 v[222:223], off
	s_add_i32 m0, s81, 0x2000
	s_add_u32 s82, s28, 0x40000
	v_lshl_add_u64 v[224:225], s[28:29], 0, v[136:137]
	s_addc_u32 s83, s29, 0
	s_add_i32 s81, s45, s35
	global_load_lds_dwordx4 v[224:225], off
	v_lshl_add_u64 v[226:227], s[82:83], 0, v[132:133]
	s_mov_b32 m0, s81
	v_lshl_add_u64 v[228:229], s[30:31], 0, v[134:135]
	global_load_lds_dwordx4 v[226:227], off
	v_lshl_add_u64 v[226:227], s[82:83], 0, v[136:137]
	s_add_i32 m0, s81, 0x2000
	s_nop 0
	global_load_lds_dwordx4 v[226:227], off
	v_lshl_add_u64 v[226:227], s[30:31], 0, v[130:131]
	s_mov_b32 m0, s9
	s_nop 0
	global_load_lds_dwordx4 v[226:227], off
	s_mov_b32 m0, s36
	s_nop 0
	global_load_lds_dwordx4 v[228:229], off
	s_waitcnt vmcnt(8)
	s_waitcnt lgkmcnt(0)
	s_barrier
	s_setprio 1
	v_mfma_f32_16x16x32_bf16 v[62:65], v[152:155], v[188:191], v[62:65]
	v_mfma_f32_16x16x32_bf16 v[58:61], v[164:167], v[188:191], v[58:61]
	v_mfma_f32_16x16x32_bf16 v[46:49], v[152:155], v[196:199], v[46:49]
	v_mfma_f32_16x16x32_bf16 v[42:45], v[164:167], v[196:199], v[42:45]
	v_mfma_f32_16x16x32_bf16 v[30:33], v[152:155], v[204:207], v[30:33]
	v_mfma_f32_16x16x32_bf16 v[26:29], v[164:167], v[204:207], v[26:29]
	v_mfma_f32_16x16x32_bf16 v[14:17], v[152:155], v[214:217], v[14:17]
	v_mfma_f32_16x16x32_bf16 v[10:13], v[164:167], v[214:217], v[10:13]
	v_mfma_f32_16x16x32_bf16 v[62:65], v[160:163], v[192:195], v[62:65]
	v_mfma_f32_16x16x32_bf16 v[58:61], v[168:171], v[192:195], v[58:61]
	v_mfma_f32_16x16x32_bf16 v[46:49], v[160:163], v[200:203], v[46:49]
	v_mfma_f32_16x16x32_bf16 v[42:45], v[168:171], v[200:203], v[42:45]
	v_mfma_f32_16x16x32_bf16 v[30:33], v[160:163], v[210:213], v[30:33]
	v_mfma_f32_16x16x32_bf16 v[26:29], v[168:171], v[210:213], v[26:29]
	v_mfma_f32_16x16x32_bf16 v[14:17], v[160:163], v[218:221], v[14:17]
	v_mfma_f32_16x16x32_bf16 v[10:13], v[168:171], v[218:221], v[10:13]
	s_setprio 0
	s_setprio 1
	v_mfma_f32_16x16x32_bf16 v[54:57], v[172:175], v[188:191], v[54:57]
	v_mfma_f32_16x16x32_bf16 v[50:53], v[180:183], v[188:191], v[50:53]
	v_mfma_f32_16x16x32_bf16 v[38:41], v[172:175], v[196:199], v[38:41]
	v_mfma_f32_16x16x32_bf16 v[34:37], v[180:183], v[196:199], v[34:37]
	v_mfma_f32_16x16x32_bf16 v[22:25], v[172:175], v[204:207], v[22:25]
	v_mfma_f32_16x16x32_bf16 v[18:21], v[180:183], v[204:207], v[18:21]
	v_mfma_f32_16x16x32_bf16 v[6:9], v[172:175], v[214:217], v[6:9]
	v_mfma_f32_16x16x32_bf16 v[2:5], v[180:183], v[214:217], v[2:5]
	v_mfma_f32_16x16x32_bf16 v[54:57], v[176:179], v[192:195], v[54:57]
	v_mfma_f32_16x16x32_bf16 v[50:53], v[184:187], v[192:195], v[50:53]
	v_mfma_f32_16x16x32_bf16 v[38:41], v[176:179], v[200:203], v[38:41]
	v_mfma_f32_16x16x32_bf16 v[34:37], v[184:187], v[200:203], v[34:37]
	v_mfma_f32_16x16x32_bf16 v[22:25], v[176:179], v[210:213], v[22:25]
	v_mfma_f32_16x16x32_bf16 v[18:21], v[184:187], v[210:213], v[18:21]
	v_mfma_f32_16x16x32_bf16 v[6:9], v[176:179], v[218:221], v[6:9]
	v_mfma_f32_16x16x32_bf16 v[2:5], v[184:187], v[218:221], v[2:5]
	s_setprio 0
	s_barrier
	s_add_i32 s81, 0, 0x18000
	v_add_u32_e32 v138, s81, v156
	s_add_i32 s82, 0, 0x1c000
	ds_read_b128 v[152:155], v138
	ds_read_b128 v[160:163], v138 offset:1024
	ds_read_b128 v[164:167], v138 offset:2048
	ds_read_b128 v[168:171], v138 offset:3072
	v_add_u32_e32 v138, 0x1000, v138
	ds_read_b128 v[172:175], v138
	ds_read_b128 v[176:179], v138 offset:1024
	ds_read_b128 v[180:183], v138 offset:2048
	ds_read_b128 v[184:187], v138 offset:3072
	s_add_u32 s30, s30, 0x40000
	s_addc_u32 s31, s31, 0
	s_mov_b32 m0, s37
	v_lshl_add_u64 v[230:231], s[30:31], 0, v[130:131]
	ds_read_b128 v[188:191], v159 offset:32768
	ds_read_b128 v[192:195], v159 offset:33792
	ds_read_b128 v[196:199], v159 offset:34816
	ds_read_b128 v[200:203], v159 offset:35840
	ds_read_b128 v[204:207], v159 offset:36864
	ds_read_b128 v[210:213], v159 offset:37888
	ds_read_b128 v[214:217], v159 offset:38912
	ds_read_b128 v[218:221], v159 offset:39936
	global_load_lds_dwordx4 v[230:231], off
	v_lshl_add_u64 v[230:231], s[30:31], 0, v[134:135]
	s_mov_b32 m0, s38
	s_nop 0
	global_load_lds_dwordx4 v[230:231], off
	s_waitcnt vmcnt(8)
	s_waitcnt lgkmcnt(0)
	s_barrier
	s_setprio 1
	s_waitcnt lgkmcnt(0)
	v_mfma_f32_16x16x32_bf16 v[126:129], v[152:155], v[188:191], v[126:129]
	v_mfma_f32_16x16x32_bf16 v[122:125], v[164:167], v[188:191], v[122:125]
	v_mfma_f32_16x16x32_bf16 v[110:113], v[152:155], v[196:199], v[110:113]
	v_mfma_f32_16x16x32_bf16 v[106:109], v[164:167], v[196:199], v[106:109]
	v_mfma_f32_16x16x32_bf16 v[94:97], v[152:155], v[204:207], v[94:97]
	v_mfma_f32_16x16x32_bf16 v[90:93], v[164:167], v[204:207], v[90:93]
	v_mfma_f32_16x16x32_bf16 v[78:81], v[152:155], v[214:217], v[78:81]
	v_mfma_f32_16x16x32_bf16 v[74:77], v[164:167], v[214:217], v[74:77]
	v_mfma_f32_16x16x32_bf16 v[126:129], v[160:163], v[192:195], v[126:129]
	v_mfma_f32_16x16x32_bf16 v[122:125], v[168:171], v[192:195], v[122:125]
	v_mfma_f32_16x16x32_bf16 v[110:113], v[160:163], v[200:203], v[110:113]
	v_mfma_f32_16x16x32_bf16 v[106:109], v[168:171], v[200:203], v[106:109]
	v_mfma_f32_16x16x32_bf16 v[94:97], v[160:163], v[210:213], v[94:97]
	v_mfma_f32_16x16x32_bf16 v[90:93], v[168:171], v[210:213], v[90:93]
	v_mfma_f32_16x16x32_bf16 v[78:81], v[160:163], v[218:221], v[78:81]
	v_mfma_f32_16x16x32_bf16 v[74:77], v[168:171], v[218:221], v[74:77]
	s_setprio 0
	s_setprio 1
	v_mfma_f32_16x16x32_bf16 v[118:121], v[172:175], v[188:191], v[118:121]
	v_mfma_f32_16x16x32_bf16 v[114:117], v[180:183], v[188:191], v[114:117]
	v_mfma_f32_16x16x32_bf16 v[102:105], v[172:175], v[196:199], v[102:105]
	v_mfma_f32_16x16x32_bf16 v[98:101], v[180:183], v[196:199], v[98:101]
	v_mfma_f32_16x16x32_bf16 v[86:89], v[172:175], v[204:207], v[86:89]
	v_mfma_f32_16x16x32_bf16 v[82:85], v[180:183], v[204:207], v[82:85]
	v_mfma_f32_16x16x32_bf16 v[70:73], v[172:175], v[214:217], v[70:73]
	v_mfma_f32_16x16x32_bf16 v[66:69], v[180:183], v[214:217], v[66:69]
	v_mfma_f32_16x16x32_bf16 v[118:121], v[176:179], v[192:195], v[118:121]
	v_mfma_f32_16x16x32_bf16 v[114:117], v[184:187], v[192:195], v[114:117]
	v_mfma_f32_16x16x32_bf16 v[102:105], v[176:179], v[200:203], v[102:105]
	v_mfma_f32_16x16x32_bf16 v[98:101], v[184:187], v[200:203], v[98:101]
	v_mfma_f32_16x16x32_bf16 v[86:89], v[176:179], v[210:213], v[86:89]
	v_mfma_f32_16x16x32_bf16 v[82:85], v[184:187], v[210:213], v[82:85]
	v_mfma_f32_16x16x32_bf16 v[70:73], v[176:179], v[218:221], v[70:73]
	v_mfma_f32_16x16x32_bf16 v[66:69], v[184:187], v[218:221], v[66:69]
	s_setprio 0
	s_barrier
	s_add_i32 s30, s81, s35
	v_lshl_add_u64 v[222:223], v[222:223], 0, s[14:15]
	s_mov_b32 m0, s30
	ds_read_b128 v[188:191], v159 offset:49152
	ds_read_b128 v[192:195], v159 offset:50176
	ds_read_b128 v[196:199], v159 offset:51200
	ds_read_b128 v[200:203], v159 offset:52224
	ds_read_b128 v[204:207], v159 offset:53248
	ds_read_b128 v[210:213], v159 offset:54272
	ds_read_b128 v[214:217], v159 offset:55296
	ds_read_b128 v[218:221], v159 offset:56320
	global_load_lds_dwordx4 v[222:223], off
	s_add_i32 m0, s30, 0x2000
	s_add_u32 s28, s28, 0x40080
	v_lshl_add_u64 v[222:223], v[224:225], 0, s[14:15]
	s_addc_u32 s29, s29, 0
	s_add_i32 s30, s82, s35
	global_load_lds_dwordx4 v[222:223], off
	v_lshl_add_u64 v[222:223], s[28:29], 0, v[132:133]
	s_mov_b32 m0, s30
	s_nop 0
	global_load_lds_dwordx4 v[222:223], off
	v_lshl_add_u64 v[222:223], s[28:29], 0, v[136:137]
	s_add_i32 m0, s30, 0x2000
	s_nop 0
	global_load_lds_dwordx4 v[222:223], off
	v_lshl_add_u64 v[222:223], v[226:227], 0, s[14:15]
	s_mov_b32 m0, s40
	s_nop 0
	global_load_lds_dwordx4 v[222:223], off
	v_lshl_add_u64 v[222:223], v[228:229], 0, s[14:15]
	s_mov_b32 m0, s41
	s_nop 0
	global_load_lds_dwordx4 v[222:223], off
	s_waitcnt vmcnt(8)
	s_waitcnt lgkmcnt(0)
	s_barrier
	s_setprio 1
	s_waitcnt lgkmcnt(0)
	v_mfma_f32_16x16x32_bf16 v[62:65], v[152:155], v[188:191], v[62:65]
	v_mfma_f32_16x16x32_bf16 v[58:61], v[164:167], v[188:191], v[58:61]
	v_mfma_f32_16x16x32_bf16 v[46:49], v[152:155], v[196:199], v[46:49]
	v_mfma_f32_16x16x32_bf16 v[42:45], v[164:167], v[196:199], v[42:45]
	v_mfma_f32_16x16x32_bf16 v[30:33], v[152:155], v[204:207], v[30:33]
	v_mfma_f32_16x16x32_bf16 v[26:29], v[164:167], v[204:207], v[26:29]
	v_mfma_f32_16x16x32_bf16 v[14:17], v[152:155], v[214:217], v[14:17]
	v_mfma_f32_16x16x32_bf16 v[10:13], v[164:167], v[214:217], v[10:13]
	v_mfma_f32_16x16x32_bf16 v[62:65], v[160:163], v[192:195], v[62:65]
	v_mfma_f32_16x16x32_bf16 v[58:61], v[168:171], v[192:195], v[58:61]
	v_mfma_f32_16x16x32_bf16 v[46:49], v[160:163], v[200:203], v[46:49]
	v_mfma_f32_16x16x32_bf16 v[42:45], v[168:171], v[200:203], v[42:45]
	v_mfma_f32_16x16x32_bf16 v[30:33], v[160:163], v[210:213], v[30:33]
	v_mfma_f32_16x16x32_bf16 v[26:29], v[168:171], v[210:213], v[26:29]
	v_mfma_f32_16x16x32_bf16 v[14:17], v[160:163], v[218:221], v[14:17]
	v_mfma_f32_16x16x32_bf16 v[10:13], v[168:171], v[218:221], v[10:13]
	s_setprio 0
	s_setprio 1
	v_mfma_f32_16x16x32_bf16 v[54:57], v[172:175], v[188:191], v[54:57]
	v_mfma_f32_16x16x32_bf16 v[50:53], v[180:183], v[188:191], v[50:53]
	v_mfma_f32_16x16x32_bf16 v[38:41], v[172:175], v[196:199], v[38:41]
	v_mfma_f32_16x16x32_bf16 v[34:37], v[180:183], v[196:199], v[34:37]
	v_mfma_f32_16x16x32_bf16 v[22:25], v[172:175], v[204:207], v[22:25]
	v_mfma_f32_16x16x32_bf16 v[18:21], v[180:183], v[204:207], v[18:21]
	v_mfma_f32_16x16x32_bf16 v[6:9], v[172:175], v[214:217], v[6:9]
	v_mfma_f32_16x16x32_bf16 v[2:5], v[180:183], v[214:217], v[2:5]
	v_mfma_f32_16x16x32_bf16 v[54:57], v[176:179], v[192:195], v[54:57]
	v_mfma_f32_16x16x32_bf16 v[50:53], v[184:187], v[192:195], v[50:53]
	v_mfma_f32_16x16x32_bf16 v[38:41], v[176:179], v[200:203], v[38:41]
	v_mfma_f32_16x16x32_bf16 v[34:37], v[184:187], v[200:203], v[34:37]
	v_mfma_f32_16x16x32_bf16 v[22:25], v[176:179], v[210:213], v[22:25]
	v_mfma_f32_16x16x32_bf16 v[18:21], v[184:187], v[210:213], v[18:21]
	v_mfma_f32_16x16x32_bf16 v[6:9], v[176:179], v[218:221], v[6:9]
	v_mfma_f32_16x16x32_bf16 v[2:5], v[184:187], v[218:221], v[2:5]
	s_setprio 0
	s_barrier
	s_add_i32 s80, s80, 2
	s_add_u32 s26, s26, 0x100
	s_addc_u32 s27, s27, 0
	s_add_u32 s58, s58, 0x100
	s_addc_u32 s59, s59, 0
	s_cmp_gt_u32 s80, 13
	s_cbranch_scc0 .LBB0_374
	s_and_b64 vcc, exec, s[16:17]
	s_cbranch_vccz .LBB0_377
	s_barrier

.LBB0_1381:
	ds_read_b128 v[130:133], v215
	ds_read_b128 v[134:137], v215 offset:1024
	ds_read_b128 v[138:141], v215 offset:2048
	ds_read_b128 v[142:145], v215 offset:3072
	ds_read_b128 v[146:149], v216
	ds_read_b128 v[150:153], v216 offset:1024
	ds_read_b128 v[154:157], v216 offset:2048
	ds_read_b128 v[158:161], v216 offset:3072
	s_add_u32 s30, s28, 0xfffc0080
	s_addc_u32 s31, s29, -1
	s_cmp_eq_u32 s66, 12
	s_cselect_b32 s35, s21, s31
	s_cselect_b32 s34, s27, s30
	s_cselect_b32 s31, s19, s65
	s_cselect_b32 s30, s63, s64
	v_lshl_add_u64 v[224:225], s[28:29], 0, v[188:189]
	s_add_i32 m0, s40, 0xc000
	ds_read_b128 v[162:165], v217
	ds_read_b128 v[166:169], v217 offset:1024
	ds_read_b128 v[170:173], v217 offset:2048
	ds_read_b128 v[174:177], v217 offset:3072
	ds_read_b128 v[196:199], v217 offset:4096
	ds_read_b128 v[200:203], v217 offset:5120
	ds_read_b128 v[204:207], v217 offset:6144
	ds_read_b128 v[220:223], v217 offset:7168
	global_load_lds_dwordx4 v[224:225], off
	v_lshl_add_u64 v[224:225], s[28:29], 0, v[190:191]
	s_add_i32 m0, s40, 0xe000
	s_nop 0
	global_load_lds_dwordx4 v[224:225], off
	s_waitcnt vmcnt(8)
	s_waitcnt lgkmcnt(0)
	s_barrier
	s_setprio 1
	v_mfma_f32_16x16x32_bf16 v[126:129], v[130:133], v[162:165], v[126:129]
	v_mfma_f32_16x16x32_bf16 v[122:125], v[138:141], v[162:165], v[122:125]
	v_mfma_f32_16x16x32_bf16 v[110:113], v[130:133], v[170:173], v[110:113]
	v_mfma_f32_16x16x32_bf16 v[106:109], v[138:141], v[170:173], v[106:109]
	v_mfma_f32_16x16x32_bf16 v[94:97], v[130:133], v[196:199], v[94:97]
	v_mfma_f32_16x16x32_bf16 v[90:93], v[138:141], v[196:199], v[90:93]
	v_mfma_f32_16x16x32_bf16 v[78:81], v[130:133], v[204:207], v[78:81]
	v_mfma_f32_16x16x32_bf16 v[74:77], v[138:141], v[204:207], v[74:77]
	v_mfma_f32_16x16x32_bf16 v[126:129], v[134:137], v[166:169], v[126:129]
	v_mfma_f32_16x16x32_bf16 v[122:125], v[142:145], v[166:169], v[122:125]
	v_mfma_f32_16x16x32_bf16 v[110:113], v[134:137], v[174:177], v[110:113]
	v_mfma_f32_16x16x32_bf16 v[106:109], v[142:145], v[174:177], v[106:109]
	v_mfma_f32_16x16x32_bf16 v[94:97], v[134:137], v[200:203], v[94:97]
	v_mfma_f32_16x16x32_bf16 v[90:93], v[142:145], v[200:203], v[90:93]
	v_mfma_f32_16x16x32_bf16 v[78:81], v[134:137], v[220:223], v[78:81]
	v_mfma_f32_16x16x32_bf16 v[74:77], v[142:145], v[220:223], v[74:77]
	s_setprio 0
	s_setprio 1
	v_mfma_f32_16x16x32_bf16 v[118:121], v[146:149], v[162:165], v[118:121]
	v_mfma_f32_16x16x32_bf16 v[114:117], v[154:157], v[162:165], v[114:117]
	v_mfma_f32_16x16x32_bf16 v[102:105], v[146:149], v[170:173], v[102:105]
	v_mfma_f32_16x16x32_bf16 v[98:101], v[154:157], v[170:173], v[98:101]
	v_mfma_f32_16x16x32_bf16 v[86:89], v[146:149], v[196:199], v[86:89]
	v_mfma_f32_16x16x32_bf16 v[82:85], v[154:157], v[196:199], v[82:85]
	v_mfma_f32_16x16x32_bf16 v[70:73], v[146:149], v[204:207], v[70:73]
	v_mfma_f32_16x16x32_bf16 v[66:69], v[154:157], v[204:207], v[66:69]
	v_mfma_f32_16x16x32_bf16 v[118:121], v[150:153], v[166:169], v[118:121]
	v_mfma_f32_16x16x32_bf16 v[114:117], v[158:161], v[166:169], v[114:117]
	v_mfma_f32_16x16x32_bf16 v[102:105], v[150:153], v[174:177], v[102:105]
	v_mfma_f32_16x16x32_bf16 v[98:101], v[158:161], v[174:177], v[98:101]
	v_mfma_f32_16x16x32_bf16 v[86:89], v[150:153], v[200:203], v[86:89]
	v_mfma_f32_16x16x32_bf16 v[82:85], v[158:161], v[200:203], v[82:85]
	v_mfma_f32_16x16x32_bf16 v[70:73], v[150:153], v[220:223], v[70:73]
	v_mfma_f32_16x16x32_bf16 v[66:69], v[158:161], v[220:223], v[66:69]
	s_setprio 0
	s_barrier
	s_add_i32 s67, s56, s39
	v_lshl_add_u64 v[224:225], s[30:31], 0, v[182:183]
	s_mov_b32 m0, s67
	ds_read_b128 v[162:165], v217 offset:16384
	ds_read_b128 v[166:169], v217 offset:17408
	ds_read_b128 v[170:173], v217 offset:18432
	ds_read_b128 v[174:177], v217 offset:19456
	ds_read_b128 v[196:199], v217 offset:20480
	ds_read_b128 v[200:203], v217 offset:21504
	ds_read_b128 v[204:207], v217 offset:22528
	ds_read_b128 v[220:223], v217 offset:23552
	global_load_lds_dwordx4 v[224:225], off
	s_add_i32 m0, s67, 0x2000
	s_add_u32 s68, s30, 0x40000
	v_lshl_add_u64 v[226:227], s[30:31], 0, v[186:187]
	s_addc_u32 s69, s31, 0
	s_add_i32 s67, s57, s39
	global_load_lds_dwordx4 v[226:227], off
	v_lshl_add_u64 v[228:229], s[68:69], 0, v[182:183]
	s_mov_b32 m0, s67
	v_lshl_add_u64 v[230:231], s[34:35], 0, v[184:185]
	global_load_lds_dwordx4 v[228:229], off
	v_lshl_add_u64 v[228:229], s[68:69], 0, v[186:187]
	s_add_i32 m0, s67, 0x2000
	s_nop 0
	global_load_lds_dwordx4 v[228:229], off
	v_lshl_add_u64 v[228:229], s[34:35], 0, v[180:181]
	s_mov_b32 m0, s40
	s_nop 0
	global_load_lds_dwordx4 v[228:229], off
	s_mov_b32 m0, s41
	s_nop 0
	global_load_lds_dwordx4 v[230:231], off
	s_waitcnt vmcnt(8)
	s_waitcnt lgkmcnt(0)
	s_barrier
	s_setprio 1
	v_mfma_f32_16x16x32_bf16 v[62:65], v[130:133], v[162:165], v[62:65]
	v_mfma_f32_16x16x32_bf16 v[58:61], v[138:141], v[162:165], v[58:61]
	v_mfma_f32_16x16x32_bf16 v[46:49], v[130:133], v[170:173], v[46:49]
	v_mfma_f32_16x16x32_bf16 v[42:45], v[138:141], v[170:173], v[42:45]
	v_mfma_f32_16x16x32_bf16 v[30:33], v[130:133], v[196:199], v[30:33]
	v_mfma_f32_16x16x32_bf16 v[26:29], v[138:141], v[196:199], v[26:29]
	v_mfma_f32_16x16x32_bf16 v[14:17], v[130:133], v[204:207], v[14:17]
	v_mfma_f32_16x16x32_bf16 v[10:13], v[138:141], v[204:207], v[10:13]
	v_mfma_f32_16x16x32_bf16 v[62:65], v[134:137], v[166:169], v[62:65]
	v_mfma_f32_16x16x32_bf16 v[58:61], v[142:145], v[166:169], v[58:61]
	v_mfma_f32_16x16x32_bf16 v[46:49], v[134:137], v[174:177], v[46:49]
	v_mfma_f32_16x16x32_bf16 v[42:45], v[142:145], v[174:177], v[42:45]
	v_mfma_f32_16x16x32_bf16 v[30:33], v[134:137], v[200:203], v[30:33]
	v_mfma_f32_16x16x32_bf16 v[26:29], v[142:145], v[200:203], v[26:29]
	v_mfma_f32_16x16x32_bf16 v[14:17], v[134:137], v[220:223], v[14:17]
	v_mfma_f32_16x16x32_bf16 v[10:13], v[142:145], v[220:223], v[10:13]
	s_setprio 0
	s_setprio 1
	v_mfma_f32_16x16x32_bf16 v[54:57], v[146:149], v[162:165], v[54:57]
	v_mfma_f32_16x16x32_bf16 v[50:53], v[154:157], v[162:165], v[50:53]
	v_mfma_f32_16x16x32_bf16 v[38:41], v[146:149], v[170:173], v[38:41]
	v_mfma_f32_16x16x32_bf16 v[34:37], v[154:157], v[170:173], v[34:37]
	v_mfma_f32_16x16x32_bf16 v[22:25], v[146:149], v[196:199], v[22:25]
	v_mfma_f32_16x16x32_bf16 v[18:21], v[154:157], v[196:199], v[18:21]
	v_mfma_f32_16x16x32_bf16 v[6:9], v[146:149], v[204:207], v[6:9]
	v_mfma_f32_16x16x32_bf16 v[2:5], v[154:157], v[204:207], v[2:5]
	v_mfma_f32_16x16x32_bf16 v[54:57], v[150:153], v[166:169], v[54:57]
	v_mfma_f32_16x16x32_bf16 v[50:53], v[158:161], v[166:169], v[50:53]
	v_mfma_f32_16x16x32_bf16 v[38:41], v[150:153], v[174:177], v[38:41]
	v_mfma_f32_16x16x32_bf16 v[34:37], v[158:161], v[174:177], v[34:37]
	v_mfma_f32_16x16x32_bf16 v[22:25], v[150:153], v[200:203], v[22:25]
	v_mfma_f32_16x16x32_bf16 v[18:21], v[158:161], v[200:203], v[18:21]
	v_mfma_f32_16x16x32_bf16 v[6:9], v[150:153], v[220:223], v[6:9]
	v_mfma_f32_16x16x32_bf16 v[2:5], v[158:161], v[220:223], v[2:5]
	s_setprio 0
	s_barrier
	s_add_i32 s67, 0, 0x18000
	s_add_i32 s68, 0, 0x1c000
	v_add_u32_e32 v142, s67, v213
	v_add_u32_e32 v158, s68, v213
	ds_read_b128 v[130:133], v142
	ds_read_b128 v[134:137], v142 offset:1024
	ds_read_b128 v[138:141], v142 offset:2048
	ds_read_b128 v[142:145], v142 offset:3072
	ds_read_b128 v[146:149], v158
	ds_read_b128 v[150:153], v158 offset:1024
	ds_read_b128 v[154:157], v158 offset:2048
	ds_read_b128 v[158:161], v158 offset:3072
	s_add_u32 s34, s34, 0x40000
	s_addc_u32 s35, s35, 0
	s_mov_b32 m0, s42
	v_lshl_add_u64 v[232:233], s[34:35], 0, v[180:181]
	ds_read_b128 v[162:165], v217 offset:32768
	ds_read_b128 v[166:169], v217 offset:33792
	ds_read_b128 v[170:173], v217 offset:34816
	ds_read_b128 v[174:177], v217 offset:35840
	ds_read_b128 v[196:199], v217 offset:36864
	ds_read_b128 v[200:203], v217 offset:37888
	ds_read_b128 v[204:207], v217 offset:38912
	ds_read_b128 v[220:223], v217 offset:39936
	global_load_lds_dwordx4 v[232:233], off
	v_lshl_add_u64 v[232:233], s[34:35], 0, v[184:185]
	s_mov_b32 m0, s43
	s_nop 0
	global_load_lds_dwordx4 v[232:233], off
	s_waitcnt vmcnt(8)
	s_waitcnt lgkmcnt(0)
	s_barrier
	s_setprio 1
	v_mfma_f32_16x16x32_bf16 v[126:129], v[130:133], v[162:165], v[126:129]
	v_mfma_f32_16x16x32_bf16 v[122:125], v[138:141], v[162:165], v[122:125]
	v_mfma_f32_16x16x32_bf16 v[110:113], v[130:133], v[170:173], v[110:113]
	v_mfma_f32_16x16x32_bf16 v[106:109], v[138:141], v[170:173], v[106:109]
	v_mfma_f32_16x16x32_bf16 v[94:97], v[130:133], v[196:199], v[94:97]
	v_mfma_f32_16x16x32_bf16 v[90:93], v[138:141], v[196:199], v[90:93]
	v_mfma_f32_16x16x32_bf16 v[78:81], v[130:133], v[204:207], v[78:81]
	v_mfma_f32_16x16x32_bf16 v[74:77], v[138:141], v[204:207], v[74:77]
	v_mfma_f32_16x16x32_bf16 v[126:129], v[134:137], v[166:169], v[126:129]
	v_mfma_f32_16x16x32_bf16 v[122:125], v[142:145], v[166:169], v[122:125]
	v_mfma_f32_16x16x32_bf16 v[110:113], v[134:137], v[174:177], v[110:113]
	v_mfma_f32_16x16x32_bf16 v[106:109], v[142:145], v[174:177], v[106:109]
	v_mfma_f32_16x16x32_bf16 v[94:97], v[134:137], v[200:203], v[94:97]
	v_mfma_f32_16x16x32_bf16 v[90:93], v[142:145], v[200:203], v[90:93]
	v_mfma_f32_16x16x32_bf16 v[78:81], v[134:137], v[220:223], v[78:81]
	v_mfma_f32_16x16x32_bf16 v[74:77], v[142:145], v[220:223], v[74:77]
	s_setprio 0
	s_setprio 1
	v_mfma_f32_16x16x32_bf16 v[118:121], v[146:149], v[162:165], v[118:121]
	v_mfma_f32_16x16x32_bf16 v[114:117], v[154:157], v[162:165], v[114:117]
	v_mfma_f32_16x16x32_bf16 v[102:105], v[146:149], v[170:173], v[102:105]
	v_mfma_f32_16x16x32_bf16 v[98:101], v[154:157], v[170:173], v[98:101]
	v_mfma_f32_16x16x32_bf16 v[86:89], v[146:149], v[196:199], v[86:89]
	v_mfma_f32_16x16x32_bf16 v[82:85], v[154:157], v[196:199], v[82:85]
	v_mfma_f32_16x16x32_bf16 v[70:73], v[146:149], v[204:207], v[70:73]
	v_mfma_f32_16x16x32_bf16 v[66:69], v[154:157], v[204:207], v[66:69]
	v_mfma_f32_16x16x32_bf16 v[118:121], v[150:153], v[166:169], v[118:121]
	v_mfma_f32_16x16x32_bf16 v[114:117], v[158:161], v[166:169], v[114:117]
	v_mfma_f32_16x16x32_bf16 v[102:105], v[150:153], v[174:177], v[102:105]
	v_mfma_f32_16x16x32_bf16 v[98:101], v[158:161], v[174:177], v[98:101]
	v_mfma_f32_16x16x32_bf16 v[86:89], v[150:153], v[200:203], v[86:89]
	v_mfma_f32_16x16x32_bf16 v[82:85], v[158:161], v[200:203], v[82:85]
	v_mfma_f32_16x16x32_bf16 v[70:73], v[150:153], v[220:223], v[70:73]
	v_mfma_f32_16x16x32_bf16 v[66:69], v[158:161], v[220:223], v[66:69]
	s_setprio 0
	s_barrier
	s_add_i32 s34, s67, s39
	v_lshl_add_u64 v[224:225], v[224:225], 0, s[14:15]
	s_mov_b32 m0, s34
	ds_read_b128 v[162:165], v217 offset:49152
	ds_read_b128 v[166:169], v217 offset:50176
	ds_read_b128 v[170:173], v217 offset:51200
	ds_read_b128 v[174:177], v217 offset:52224
	ds_read_b128 v[196:199], v217 offset:53248
	ds_read_b128 v[200:203], v217 offset:54272
	ds_read_b128 v[204:207], v217 offset:55296
	ds_read_b128 v[220:223], v217 offset:56320
	global_load_lds_dwordx4 v[224:225], off
	s_add_i32 m0, s34, 0x2000
	s_add_u32 s30, s30, 0x40080
	v_lshl_add_u64 v[224:225], v[226:227], 0, s[14:15]
	s_addc_u32 s31, s31, 0
	s_add_i32 s34, s68, s39
	global_load_lds_dwordx4 v[224:225], off
	v_lshl_add_u64 v[224:225], s[30:31], 0, v[182:183]
	s_mov_b32 m0, s34
	s_nop 0
	global_load_lds_dwordx4 v[224:225], off
	v_lshl_add_u64 v[224:225], s[30:31], 0, v[186:187]
	s_add_i32 m0, s34, 0x2000
	s_nop 0
	global_load_lds_dwordx4 v[224:225], off
	v_lshl_add_u64 v[224:225], v[228:229], 0, s[14:15]
	s_mov_b32 m0, s52
	s_nop 0
	global_load_lds_dwordx4 v[224:225], off
	v_lshl_add_u64 v[224:225], v[230:231], 0, s[14:15]
	s_mov_b32 m0, s53
	s_nop 0
	global_load_lds_dwordx4 v[224:225], off
	s_waitcnt vmcnt(8)
	s_waitcnt lgkmcnt(0)
	s_barrier
	s_setprio 1
	s_waitcnt lgkmcnt(0)
	v_mfma_f32_16x16x32_bf16 v[62:65], v[130:133], v[162:165], v[62:65]
	v_mfma_f32_16x16x32_bf16 v[58:61], v[138:141], v[162:165], v[58:61]
	v_mfma_f32_16x16x32_bf16 v[46:49], v[130:133], v[170:173], v[46:49]
	v_mfma_f32_16x16x32_bf16 v[42:45], v[138:141], v[170:173], v[42:45]
	v_mfma_f32_16x16x32_bf16 v[30:33], v[130:133], v[196:199], v[30:33]
	v_mfma_f32_16x16x32_bf16 v[26:29], v[138:141], v[196:199], v[26:29]
	v_mfma_f32_16x16x32_bf16 v[14:17], v[130:133], v[204:207], v[14:17]
	v_mfma_f32_16x16x32_bf16 v[10:13], v[138:141], v[204:207], v[10:13]
	v_mfma_f32_16x16x32_bf16 v[62:65], v[134:137], v[166:169], v[62:65]
	v_mfma_f32_16x16x32_bf16 v[58:61], v[142:145], v[166:169], v[58:61]
	v_mfma_f32_16x16x32_bf16 v[46:49], v[134:137], v[174:177], v[46:49]
	v_mfma_f32_16x16x32_bf16 v[42:45], v[142:145], v[174:177], v[42:45]
	v_mfma_f32_16x16x32_bf16 v[30:33], v[134:137], v[200:203], v[30:33]
	v_mfma_f32_16x16x32_bf16 v[26:29], v[142:145], v[200:203], v[26:29]
	v_mfma_f32_16x16x32_bf16 v[14:17], v[134:137], v[220:223], v[14:17]
	v_mfma_f32_16x16x32_bf16 v[10:13], v[142:145], v[220:223], v[10:13]
	s_setprio 0
	s_setprio 1
	v_mfma_f32_16x16x32_bf16 v[54:57], v[146:149], v[162:165], v[54:57]
	v_mfma_f32_16x16x32_bf16 v[50:53], v[154:157], v[162:165], v[50:53]
	v_mfma_f32_16x16x32_bf16 v[38:41], v[146:149], v[170:173], v[38:41]
	v_mfma_f32_16x16x32_bf16 v[34:37], v[154:157], v[170:173], v[34:37]
	v_mfma_f32_16x16x32_bf16 v[22:25], v[146:149], v[196:199], v[22:25]
	v_mfma_f32_16x16x32_bf16 v[18:21], v[154:157], v[196:199], v[18:21]
	v_mfma_f32_16x16x32_bf16 v[6:9], v[146:149], v[204:207], v[6:9]
	v_mfma_f32_16x16x32_bf16 v[2:5], v[154:157], v[204:207], v[2:5]
	v_mfma_f32_16x16x32_bf16 v[54:57], v[150:153], v[166:169], v[54:57]
	v_mfma_f32_16x16x32_bf16 v[50:53], v[158:161], v[166:169], v[50:53]
	v_mfma_f32_16x16x32_bf16 v[38:41], v[150:153], v[174:177], v[38:41]
	v_mfma_f32_16x16x32_bf16 v[34:37], v[158:161], v[174:177], v[34:37]
	v_mfma_f32_16x16x32_bf16 v[22:25], v[150:153], v[200:203], v[22:25]
	v_mfma_f32_16x16x32_bf16 v[18:21], v[158:161], v[200:203], v[18:21]
	v_mfma_f32_16x16x32_bf16 v[6:9], v[150:153], v[220:223], v[6:9]
	v_mfma_f32_16x16x32_bf16 v[2:5], v[158:161], v[220:223], v[2:5]
	s_setprio 0
	s_barrier
	s_add_i32 s66, s66, 2
	s_add_u32 s28, s28, 0x100
	s_addc_u32 s29, s29, 0
	s_add_u32 s64, s64, 0x100
	s_addc_u32 s65, s65, 0
	s_cmp_gt_u32 s66, 13
	s_cbranch_scc0 .LBB0_1381
	s_and_b64 vcc, exec, s[16:17]
	s_cbranch_vccz .LBB0_1384
	s_barrier

.LBB0_1416:
	ds_read_b128 v[2:5], v135
	ds_read_b128 v[6:9], v135 offset:1024
	ds_read_b128 v[10:13], v135 offset:2048
	ds_read_b128 v[14:17], v135 offset:3072
	ds_read_b128 v[18:21], v136
	ds_read_b128 v[22:25], v136 offset:1024
	ds_read_b128 v[26:29], v136 offset:2048
	ds_read_b128 v[30:33], v136 offset:3072
	s_add_u32 s30, s30, 0x40080
	s_addc_u32 s31, s31, 0
	s_mov_b32 m0, s44
	v_lshl_add_u64 v[66:67], s[30:31], 0, v[180:181]
	ds_read_b128 v[34:37], v137
	ds_read_b128 v[38:41], v137 offset:1024
	ds_read_b128 v[42:45], v137 offset:2048
	ds_read_b128 v[46:49], v137 offset:3072
	ds_read_b128 v[50:53], v137 offset:4096
	ds_read_b128 v[54:57], v137 offset:5120
	ds_read_b128 v[58:61], v137 offset:6144
	ds_read_b128 v[62:65], v137 offset:7168
	global_load_lds_dwordx4 v[66:67], off
	v_lshl_add_u64 v[66:67], s[30:31], 0, v[184:185]
	s_mov_b32 m0, s45
	s_nop 0
	global_load_lds_dwordx4 v[66:67], off
	s_waitcnt vmcnt(8)
	s_waitcnt lgkmcnt(0)
	s_barrier
	s_setprio 1
	s_waitcnt lgkmcnt(0)
	v_mfma_f32_16x16x32_bf16 v[90:93], v[2:5], v[58:61], 0
	v_mfma_f32_16x16x32_bf16 v[66:69], v[2:5], v[34:37], 0
	v_mfma_f32_16x16x32_bf16 v[70:73], v[10:13], v[34:37], 0
	v_mfma_f32_16x16x32_bf16 v[74:77], v[2:5], v[42:45], 0
	v_mfma_f32_16x16x32_bf16 v[78:81], v[10:13], v[42:45], 0
	v_mfma_f32_16x16x32_bf16 v[82:85], v[2:5], v[50:53], 0
	v_mfma_f32_16x16x32_bf16 v[86:89], v[10:13], v[50:53], 0
	v_mfma_f32_16x16x32_bf16 v[94:97], v[6:9], v[62:65], v[90:93]
	v_mfma_f32_16x16x32_bf16 v[90:93], v[10:13], v[58:61], 0
	v_mfma_f32_16x16x32_bf16 v[66:69], v[6:9], v[38:41], v[66:69]
	v_mfma_f32_16x16x32_bf16 v[70:73], v[14:17], v[38:41], v[70:73]
	v_mfma_f32_16x16x32_bf16 v[74:77], v[6:9], v[46:49], v[74:77]
	v_mfma_f32_16x16x32_bf16 v[78:81], v[14:17], v[46:49], v[78:81]
	v_mfma_f32_16x16x32_bf16 v[82:85], v[6:9], v[54:57], v[82:85]
	v_mfma_f32_16x16x32_bf16 v[86:89], v[14:17], v[54:57], v[86:89]
	v_mfma_f32_16x16x32_bf16 v[102:105], v[14:17], v[62:65], v[90:93]
	s_setprio 0
	s_setprio 1
	v_mfma_f32_16x16x32_bf16 v[90:93], v[18:21], v[34:37], 0
	v_mfma_f32_16x16x32_bf16 v[34:37], v[26:29], v[34:37], 0
	v_mfma_f32_16x16x32_bf16 v[110:113], v[22:25], v[38:41], v[90:93]
	v_mfma_f32_16x16x32_bf16 v[34:37], v[30:33], v[38:41], v[34:37]
	v_mfma_f32_16x16x32_bf16 v[38:41], v[18:21], v[42:45], 0
	v_mfma_f32_16x16x32_bf16 v[42:45], v[26:29], v[42:45], 0
	v_mfma_f32_16x16x32_bf16 v[38:41], v[22:25], v[46:49], v[38:41]
	v_mfma_f32_16x16x32_bf16 v[42:45], v[30:33], v[46:49], v[42:45]
	v_mfma_f32_16x16x32_bf16 v[46:49], v[18:21], v[50:53], 0
	v_mfma_f32_16x16x32_bf16 v[50:53], v[26:29], v[50:53], 0
	v_mfma_f32_16x16x32_bf16 v[46:49], v[22:25], v[54:57], v[46:49]
	v_mfma_f32_16x16x32_bf16 v[54:57], v[30:33], v[54:57], v[50:53]
	v_mfma_f32_16x16x32_bf16 v[50:53], v[18:21], v[58:61], 0
	v_mfma_f32_16x16x32_bf16 v[138:141], v[22:25], v[62:65], v[50:53]
	v_mfma_f32_16x16x32_bf16 v[50:53], v[26:29], v[58:61], 0
	v_mfma_f32_16x16x32_bf16 v[142:145], v[30:33], v[62:65], v[50:53]
	s_setprio 0
	s_barrier
	s_mov_b32 m0, s48
	v_lshl_add_u64 v[130:131], s[4:5], 0, v[182:183]
	s_add_u32 s30, s4, 0x40000
	s_nop 1
	ds_read_b128 v[50:53], v137 offset:16384
	ds_read_b128 v[58:61], v137 offset:17408
	ds_read_b128 v[62:65], v137 offset:18432
	ds_read_b128 v[90:93], v137 offset:19456
	ds_read_b128 v[98:101], v137 offset:20480
	ds_read_b128 v[106:109], v137 offset:21504
	ds_read_b128 v[114:117], v137 offset:22528
	ds_read_b128 v[118:121], v137 offset:23552
	global_load_lds_dwordx4 v[130:131], off
	v_lshl_add_u64 v[250:251], s[4:5], 0, v[186:187]
	s_mov_b32 m0, s49
	s_addc_u32 s31, s5, 0
	global_load_lds_dwordx4 v[250:251], off
	v_lshl_add_u64 v[122:123], s[30:31], 0, v[182:183]
	s_mov_b32 m0, s52
	v_lshl_add_u64 v[252:253], s[22:23], 0, v[180:181]
	global_load_lds_dwordx4 v[122:123], off
	v_lshl_add_u64 v[122:123], s[30:31], 0, v[186:187]
	s_mov_b32 m0, s53
	v_lshl_add_u64 v[208:209], s[22:23], 0, v[184:185]
	global_load_lds_dwordx4 v[122:123], off
	s_mov_b32 m0, s25
	s_nop 0
	global_load_lds_dwordx4 v[252:253], off
	s_mov_b32 m0, s27
	s_nop 0
	global_load_lds_dwordx4 v[208:209], off
	s_waitcnt vmcnt(8)
	s_waitcnt lgkmcnt(0)
	s_barrier
	s_setprio 1
	v_mfma_f32_16x16x32_bf16 v[122:125], v[2:5], v[50:53], 0
	v_mfma_f32_16x16x32_bf16 v[146:149], v[6:9], v[58:61], v[122:125]
	v_mfma_f32_16x16x32_bf16 v[122:125], v[10:13], v[50:53], 0
	v_mfma_f32_16x16x32_bf16 v[150:153], v[14:17], v[58:61], v[122:125]
	v_mfma_f32_16x16x32_bf16 v[122:125], v[2:5], v[62:65], 0
	v_mfma_f32_16x16x32_bf16 v[154:157], v[6:9], v[90:93], v[122:125]
	v_mfma_f32_16x16x32_bf16 v[122:125], v[10:13], v[62:65], 0
	v_mfma_f32_16x16x32_bf16 v[158:161], v[14:17], v[90:93], v[122:125]
	v_mfma_f32_16x16x32_bf16 v[122:125], v[2:5], v[98:101], 0
	v_mfma_f32_16x16x32_bf16 v[2:5], v[2:5], v[114:117], 0
	v_mfma_f32_16x16x32_bf16 v[162:165], v[6:9], v[106:109], v[122:125]
	v_mfma_f32_16x16x32_bf16 v[2:5], v[6:9], v[118:121], v[2:5]
	v_mfma_f32_16x16x32_bf16 v[6:9], v[10:13], v[114:117], 0
	v_mfma_f32_16x16x32_bf16 v[122:125], v[10:13], v[98:101], 0
	v_mfma_f32_16x16x32_bf16 v[6:9], v[14:17], v[118:121], v[6:9]
	v_mfma_f32_16x16x32_bf16 v[166:169], v[14:17], v[106:109], v[122:125]
	s_setprio 0
	s_setprio 1
	v_mfma_f32_16x16x32_bf16 v[10:13], v[18:21], v[50:53], 0
	v_mfma_f32_16x16x32_bf16 v[14:17], v[22:25], v[58:61], v[10:13]
	v_mfma_f32_16x16x32_bf16 v[10:13], v[26:29], v[50:53], 0
	v_mfma_f32_16x16x32_bf16 v[170:173], v[30:33], v[58:61], v[10:13]
	v_mfma_f32_16x16x32_bf16 v[10:13], v[18:21], v[62:65], 0
	v_mfma_f32_16x16x32_bf16 v[174:177], v[22:25], v[90:93], v[10:13]
	v_mfma_f32_16x16x32_bf16 v[10:13], v[26:29], v[62:65], 0
	v_mfma_f32_16x16x32_bf16 v[188:191], v[30:33], v[90:93], v[10:13]
	v_mfma_f32_16x16x32_bf16 v[10:13], v[18:21], v[98:101], 0
	v_mfma_f32_16x16x32_bf16 v[192:195], v[22:25], v[106:109], v[10:13]
	v_mfma_f32_16x16x32_bf16 v[10:13], v[26:29], v[98:101], 0
	v_mfma_f32_16x16x32_bf16 v[196:199], v[30:33], v[106:109], v[10:13]
	v_mfma_f32_16x16x32_bf16 v[10:13], v[18:21], v[114:117], 0
	v_mfma_f32_16x16x32_bf16 v[200:203], v[22:25], v[118:121], v[10:13]
	v_mfma_f32_16x16x32_bf16 v[10:13], v[26:29], v[114:117], 0
	v_mfma_f32_16x16x32_bf16 v[204:207], v[30:33], v[118:121], v[10:13]
	s_setprio 0
	s_barrier
	s_add_i32 s17, 0, 0x18000
	v_add_u32_e32 v18, s17, v133
	s_add_i32 s19, 0, 0x1c000
	s_nop 1
	ds_read_b128 v[10:13], v18
	ds_read_b128 v[22:25], v18 offset:1024
	ds_read_b128 v[30:33], v18 offset:2048
	ds_read_b128 v[210:213], v18 offset:3072
	v_add_u32_e32 v18, s19, v133
	ds_read_b128 v[214:217], v18
	ds_read_b128 v[218:221], v18 offset:1024
	ds_read_b128 v[222:225], v18 offset:2048
	ds_read_b128 v[226:229], v18 offset:3072
	s_add_u32 s30, s22, 0x40000
	s_addc_u32 s31, s23, 0
	s_mov_b32 m0, s29
	v_lshl_add_u64 v[50:51], s[30:31], 0, v[180:181]
	ds_read_b128 v[18:21], v137 offset:32768
	ds_read_b128 v[26:29], v137 offset:33792
	ds_read_b128 v[62:65], v137 offset:34816
	ds_read_b128 v[230:233], v137 offset:35840
	ds_read_b128 v[234:237], v137 offset:36864
	ds_read_b128 v[238:241], v137 offset:37888
	ds_read_b128 v[242:245], v137 offset:38912
	ds_read_b128 v[246:249], v137 offset:39936
	global_load_lds_dwordx4 v[50:51], off
	v_lshl_add_u64 v[50:51], s[30:31], 0, v[184:185]
	s_mov_b32 m0, s35
	s_nop 0
	global_load_lds_dwordx4 v[50:51], off
	s_waitcnt vmcnt(8)
	s_waitcnt lgkmcnt(0)
	s_barrier
	s_setprio 1
	s_waitcnt lgkmcnt(0)
	v_mfma_f32_16x16x32_bf16 v[50:53], v[10:13], v[18:21], v[66:69]
	v_mfma_f32_16x16x32_bf16 v[122:125], v[22:25], v[26:29], v[50:53]
	v_mfma_f32_16x16x32_bf16 v[50:53], v[30:33], v[18:21], v[70:73]
	v_mfma_f32_16x16x32_bf16 v[114:117], v[210:213], v[26:29], v[50:53]
	v_mfma_f32_16x16x32_bf16 v[50:53], v[10:13], v[62:65], v[74:77]
	v_mfma_f32_16x16x32_bf16 v[106:109], v[22:25], v[230:233], v[50:53]
	v_mfma_f32_16x16x32_bf16 v[50:53], v[30:33], v[62:65], v[78:81]
	v_mfma_f32_16x16x32_bf16 v[98:101], v[210:213], v[230:233], v[50:53]
	v_mfma_f32_16x16x32_bf16 v[50:53], v[10:13], v[234:237], v[82:85]
	v_mfma_f32_16x16x32_bf16 v[90:93], v[22:25], v[238:241], v[50:53]
	v_mfma_f32_16x16x32_bf16 v[50:53], v[30:33], v[234:237], v[86:89]
	v_mfma_f32_16x16x32_bf16 v[82:85], v[210:213], v[238:241], v[50:53]
	v_mfma_f32_16x16x32_bf16 v[50:53], v[10:13], v[242:245], v[94:97]
	v_mfma_f32_16x16x32_bf16 v[58:61], v[22:25], v[246:249], v[50:53]
	v_mfma_f32_16x16x32_bf16 v[50:53], v[30:33], v[242:245], v[102:105]
	v_mfma_f32_16x16x32_bf16 v[50:53], v[210:213], v[246:249], v[50:53]
	s_setprio 0
	s_setprio 1
	v_mfma_f32_16x16x32_bf16 v[66:69], v[214:217], v[18:21], v[110:113]
	v_mfma_f32_16x16x32_bf16 v[18:21], v[222:225], v[18:21], v[34:37]
	v_mfma_f32_16x16x32_bf16 v[118:121], v[226:229], v[26:29], v[18:21]
	v_mfma_f32_16x16x32_bf16 v[18:21], v[214:217], v[62:65], v[38:41]
	v_mfma_f32_16x16x32_bf16 v[110:113], v[218:221], v[230:233], v[18:21]
	v_mfma_f32_16x16x32_bf16 v[18:21], v[222:225], v[62:65], v[42:45]
	v_mfma_f32_16x16x32_bf16 v[102:105], v[226:229], v[230:233], v[18:21]
	v_mfma_f32_16x16x32_bf16 v[18:21], v[214:217], v[234:237], v[46:49]
	v_mfma_f32_16x16x32_bf16 v[94:97], v[218:221], v[238:241], v[18:21]
	v_mfma_f32_16x16x32_bf16 v[18:21], v[222:225], v[234:237], v[54:57]
	v_mfma_f32_16x16x32_bf16 v[86:89], v[226:229], v[238:241], v[18:21]
	v_mfma_f32_16x16x32_bf16 v[18:21], v[214:217], v[242:245], v[138:141]
	v_mfma_f32_16x16x32_bf16 v[62:65], v[218:221], v[246:249], v[18:21]
	v_mfma_f32_16x16x32_bf16 v[18:21], v[222:225], v[242:245], v[142:145]
	v_mfma_f32_16x16x32_bf16 v[126:129], v[218:221], v[26:29], v[66:69]
	v_mfma_f32_16x16x32_bf16 v[54:57], v[226:229], v[246:249], v[18:21]
	s_setprio 0
	s_barrier
	s_add_i32 s17, s17, s34
	s_nop 2
	v_lshl_add_u64 v[18:19], v[130:131], 0, s[12:13]
	s_mov_b32 m0, s17
	ds_read_b128 v[38:41], v137 offset:49152
	ds_read_b128 v[46:49], v137 offset:50176
	ds_read_b128 v[138:141], v137 offset:51200
	ds_read_b128 v[142:145], v137 offset:52224
	ds_read_b128 v[230:233], v137 offset:53248
	ds_read_b128 v[234:237], v137 offset:54272
	ds_read_b128 v[238:241], v137 offset:55296
	ds_read_b128 v[242:245], v137 offset:56320
	global_load_lds_dwordx4 v[18:19], off
	s_add_i32 m0, s17, 0x2000
	s_add_u32 s30, s4, 0x40080
	v_lshl_add_u64 v[18:19], v[250:251], 0, s[12:13]
	s_addc_u32 s31, s5, 0
	s_add_i32 s17, s19, s34
	global_load_lds_dwordx4 v[18:19], off
	v_lshl_add_u64 v[18:19], s[30:31], 0, v[182:183]
	s_mov_b32 m0, s17
	s_nop 0
	global_load_lds_dwordx4 v[18:19], off
	v_lshl_add_u64 v[18:19], s[30:31], 0, v[186:187]
	s_add_i32 m0, s17, 0x2000
	s_nop 0
	global_load_lds_dwordx4 v[18:19], off
	v_lshl_add_u64 v[18:19], v[252:253], 0, s[12:13]
	s_mov_b32 m0, s41
	s_nop 0
	global_load_lds_dwordx4 v[18:19], off
	v_lshl_add_u64 v[18:19], v[208:209], 0, s[12:13]
	s_mov_b32 m0, s42
	s_nop 0
	global_load_lds_dwordx4 v[18:19], off
	s_waitcnt vmcnt(8)
	s_waitcnt lgkmcnt(0)
	s_barrier
	s_setprio 1
	v_mfma_f32_16x16x32_bf16 v[18:21], v[10:13], v[38:41], v[146:149]
	v_mfma_f32_16x16x32_bf16 v[74:77], v[22:25], v[46:49], v[18:21]
	v_mfma_f32_16x16x32_bf16 v[18:21], v[30:33], v[38:41], v[150:153]
	v_mfma_f32_16x16x32_bf16 v[66:69], v[210:213], v[46:49], v[18:21]
	v_mfma_f32_16x16x32_bf16 v[18:21], v[10:13], v[138:141], v[154:157]
	v_mfma_f32_16x16x32_bf16 v[42:45], v[22:25], v[142:145], v[18:21]
	v_mfma_f32_16x16x32_bf16 v[18:21], v[30:33], v[138:141], v[158:161]
	v_mfma_f32_16x16x32_bf16 v[34:37], v[210:213], v[142:145], v[18:21]
	v_mfma_f32_16x16x32_bf16 v[18:21], v[10:13], v[230:233], v[162:165]
	v_mfma_f32_16x16x32_bf16 v[2:5], v[10:13], v[238:241], v[2:5]
	v_mfma_f32_16x16x32_bf16 v[26:29], v[22:25], v[234:237], v[18:21]
	v_mfma_f32_16x16x32_bf16 v[18:21], v[30:33], v[230:233], v[166:169]
	v_mfma_f32_16x16x32_bf16 v[10:13], v[22:25], v[242:245], v[2:5]
	v_mfma_f32_16x16x32_bf16 v[2:5], v[30:33], v[238:241], v[6:9]
	v_mfma_f32_16x16x32_bf16 v[18:21], v[210:213], v[234:237], v[18:21]
	v_mfma_f32_16x16x32_bf16 v[2:5], v[210:213], v[242:245], v[2:5]
	s_setprio 0
	s_setprio 1
	v_mfma_f32_16x16x32_bf16 v[6:9], v[214:217], v[38:41], v[14:17]
	v_mfma_f32_16x16x32_bf16 v[78:81], v[218:221], v[46:49], v[6:9]
	v_mfma_f32_16x16x32_bf16 v[6:9], v[222:225], v[38:41], v[170:173]
	v_mfma_f32_16x16x32_bf16 v[70:73], v[226:229], v[46:49], v[6:9]
	v_mfma_f32_16x16x32_bf16 v[6:9], v[214:217], v[138:141], v[174:177]
	v_mfma_f32_16x16x32_bf16 v[46:49], v[218:221], v[142:145], v[6:9]
	v_mfma_f32_16x16x32_bf16 v[6:9], v[222:225], v[138:141], v[188:191]
	v_mfma_f32_16x16x32_bf16 v[38:41], v[226:229], v[142:145], v[6:9]
	v_mfma_f32_16x16x32_bf16 v[6:9], v[214:217], v[230:233], v[192:195]
	v_mfma_f32_16x16x32_bf16 v[30:33], v[218:221], v[234:237], v[6:9]
	v_mfma_f32_16x16x32_bf16 v[6:9], v[222:225], v[230:233], v[196:199]
	v_mfma_f32_16x16x32_bf16 v[22:25], v[226:229], v[234:237], v[6:9]
	v_mfma_f32_16x16x32_bf16 v[6:9], v[214:217], v[238:241], v[200:203]
	v_mfma_f32_16x16x32_bf16 v[14:17], v[218:221], v[242:245], v[6:9]
	v_mfma_f32_16x16x32_bf16 v[6:9], v[222:225], v[238:241], v[204:207]
	v_mfma_f32_16x16x32_bf16 v[6:9], v[226:229], v[242:245], v[6:9]
	s_setprio 0
	s_barrier
	s_andn2_b64 vcc, exec, s[14:15]
	s_cbranch_vccnz .LBB0_1418
	s_barrier

.Lp5_nozero:
.LBB0_1558:
	ds_read_b128 v[146:149], v153
	ds_read_b128 v[156:159], v153 offset:1024
	ds_read_b128 v[160:163], v153 offset:2048
	ds_read_b128 v[164:167], v153 offset:3072
	ds_read_b128 v[168:171], v154
	ds_read_b128 v[172:175], v154 offset:1024
	ds_read_b128 v[180:183], v154 offset:2048
	ds_read_b128 v[184:187], v154 offset:3072
	s_add_u32 s26, s24, 0xfffc0080
	s_addc_u32 s27, s25, -1
	s_cmp_eq_u32 s55, 12
	s_cselect_b32 s29, s17, s27
	s_cselect_b32 s28, s51, s26
	s_cselect_b32 s27, s15, s54
	s_cselect_b32 s26, s52, s53
	v_lshl_add_u64 v[176:177], s[24:25], 0, v[138:139]
	s_add_i32 m0, s23, 0xc000
	ds_read_b128 v[188:191], v155
	ds_read_b128 v[192:195], v155 offset:1024
	ds_read_b128 v[196:199], v155 offset:2048
	ds_read_b128 v[200:203], v155 offset:3072
	ds_read_b128 v[204:207], v155 offset:4096
	ds_read_b128 v[210:213], v155 offset:5120
	ds_read_b128 v[214:217], v155 offset:6144
	ds_read_b128 v[218:221], v155 offset:7168
	global_load_lds_dwordx4 v[176:177], off
	v_lshl_add_u64 v[176:177], s[24:25], 0, v[140:141]
	s_add_i32 m0, s23, 0xe000
	s_nop 0
	global_load_lds_dwordx4 v[176:177], off
	s_waitcnt vmcnt(8)
	s_waitcnt lgkmcnt(0)
	s_barrier
	s_setprio 1
	s_waitcnt lgkmcnt(0)
	v_mfma_f32_16x16x32_bf16 v[122:125], v[146:149], v[188:191], v[122:125]
	v_mfma_f32_16x16x32_bf16 v[114:117], v[160:163], v[188:191], v[114:117]
	v_mfma_f32_16x16x32_bf16 v[106:109], v[146:149], v[196:199], v[106:109]
	v_mfma_f32_16x16x32_bf16 v[98:101], v[160:163], v[196:199], v[98:101]
	v_mfma_f32_16x16x32_bf16 v[90:93], v[146:149], v[204:207], v[90:93]
	v_mfma_f32_16x16x32_bf16 v[82:85], v[160:163], v[204:207], v[82:85]
	v_mfma_f32_16x16x32_bf16 v[74:77], v[146:149], v[214:217], v[74:77]
	v_mfma_f32_16x16x32_bf16 v[70:73], v[160:163], v[214:217], v[70:73]
	v_mfma_f32_16x16x32_bf16 v[122:125], v[156:159], v[192:195], v[122:125]
	v_mfma_f32_16x16x32_bf16 v[114:117], v[164:167], v[192:195], v[114:117]
	v_mfma_f32_16x16x32_bf16 v[106:109], v[156:159], v[200:203], v[106:109]
	v_mfma_f32_16x16x32_bf16 v[98:101], v[164:167], v[200:203], v[98:101]
	v_mfma_f32_16x16x32_bf16 v[90:93], v[156:159], v[210:213], v[90:93]
	v_mfma_f32_16x16x32_bf16 v[82:85], v[164:167], v[210:213], v[82:85]
	v_mfma_f32_16x16x32_bf16 v[74:77], v[156:159], v[218:221], v[74:77]
	v_mfma_f32_16x16x32_bf16 v[70:73], v[164:167], v[218:221], v[70:73]
	s_setprio 0
	s_setprio 1
	v_mfma_f32_16x16x32_bf16 v[126:129], v[168:171], v[188:191], v[126:129]
	v_mfma_f32_16x16x32_bf16 v[118:121], v[180:183], v[188:191], v[118:121]
	v_mfma_f32_16x16x32_bf16 v[110:113], v[168:171], v[196:199], v[110:113]
	v_mfma_f32_16x16x32_bf16 v[102:105], v[180:183], v[196:199], v[102:105]
	v_mfma_f32_16x16x32_bf16 v[94:97], v[168:171], v[204:207], v[94:97]
	v_mfma_f32_16x16x32_bf16 v[86:89], v[180:183], v[204:207], v[86:89]
	v_mfma_f32_16x16x32_bf16 v[78:81], v[168:171], v[214:217], v[78:81]
	v_mfma_f32_16x16x32_bf16 v[66:69], v[180:183], v[214:217], v[66:69]
	v_mfma_f32_16x16x32_bf16 v[126:129], v[172:175], v[192:195], v[126:129]
	v_mfma_f32_16x16x32_bf16 v[118:121], v[184:187], v[192:195], v[118:121]
	v_mfma_f32_16x16x32_bf16 v[110:113], v[172:175], v[200:203], v[110:113]
	v_mfma_f32_16x16x32_bf16 v[102:105], v[184:187], v[200:203], v[102:105]
	v_mfma_f32_16x16x32_bf16 v[94:97], v[172:175], v[210:213], v[94:97]
	v_mfma_f32_16x16x32_bf16 v[86:89], v[184:187], v[210:213], v[86:89]
	v_mfma_f32_16x16x32_bf16 v[78:81], v[172:175], v[218:221], v[78:81]
	v_mfma_f32_16x16x32_bf16 v[66:69], v[184:187], v[218:221], v[66:69]
	s_setprio 0
	s_barrier
	s_add_i32 s56, s45, s35
	v_lshl_add_u64 v[176:177], s[26:27], 0, v[134:135]
	s_mov_b32 m0, s56
	ds_read_b128 v[188:191], v155 offset:16384
	ds_read_b128 v[192:195], v155 offset:17408
	ds_read_b128 v[196:199], v155 offset:18432
	ds_read_b128 v[200:203], v155 offset:19456
	ds_read_b128 v[204:207], v155 offset:20480
	ds_read_b128 v[210:213], v155 offset:21504
	ds_read_b128 v[214:217], v155 offset:22528
	ds_read_b128 v[218:221], v155 offset:23552
	global_load_lds_dwordx4 v[176:177], off
	s_add_i32 m0, s56, 0x2000
	s_add_u32 s56, s26, 0x40000
	v_lshl_add_u64 v[208:209], s[26:27], 0, v[130:131]
	s_addc_u32 s57, s27, 0
	s_add_i32 s58, s48, s35
	global_load_lds_dwordx4 v[208:209], off
	v_lshl_add_u64 v[222:223], s[56:57], 0, v[134:135]
	s_mov_b32 m0, s58
	v_lshl_add_u64 v[224:225], s[28:29], 0, v[132:133]
	global_load_lds_dwordx4 v[222:223], off
	v_lshl_add_u64 v[222:223], s[56:57], 0, v[130:131]
	s_add_i32 m0, s58, 0x2000
	s_nop 0
	global_load_lds_dwordx4 v[222:223], off
	v_lshl_add_u64 v[222:223], s[28:29], 0, v[136:137]
	s_mov_b32 m0, s23
	s_nop 0
	global_load_lds_dwordx4 v[222:223], off
	s_mov_b32 m0, s38
	s_nop 0
	global_load_lds_dwordx4 v[224:225], off
	s_waitcnt vmcnt(8)
	s_waitcnt lgkmcnt(0)
	s_barrier
	s_setprio 1
	v_mfma_f32_16x16x32_bf16 v[58:61], v[146:149], v[188:191], v[58:61]
	v_mfma_f32_16x16x32_bf16 v[54:57], v[160:163], v[188:191], v[54:57]
	v_mfma_f32_16x16x32_bf16 v[42:45], v[146:149], v[196:199], v[42:45]
	v_mfma_f32_16x16x32_bf16 v[38:41], v[160:163], v[196:199], v[38:41]
	v_mfma_f32_16x16x32_bf16 v[26:29], v[146:149], v[204:207], v[26:29]
	v_mfma_f32_16x16x32_bf16 v[22:25], v[160:163], v[204:207], v[22:25]
	v_mfma_f32_16x16x32_bf16 v[10:13], v[146:149], v[214:217], v[10:13]
	v_mfma_f32_16x16x32_bf16 v[6:9], v[160:163], v[214:217], v[6:9]
	v_mfma_f32_16x16x32_bf16 v[58:61], v[156:159], v[192:195], v[58:61]
	v_mfma_f32_16x16x32_bf16 v[54:57], v[164:167], v[192:195], v[54:57]
	v_mfma_f32_16x16x32_bf16 v[42:45], v[156:159], v[200:203], v[42:45]
	v_mfma_f32_16x16x32_bf16 v[38:41], v[164:167], v[200:203], v[38:41]
	v_mfma_f32_16x16x32_bf16 v[26:29], v[156:159], v[210:213], v[26:29]
	v_mfma_f32_16x16x32_bf16 v[22:25], v[164:167], v[210:213], v[22:25]
	v_mfma_f32_16x16x32_bf16 v[10:13], v[156:159], v[218:221], v[10:13]
	v_mfma_f32_16x16x32_bf16 v[6:9], v[164:167], v[218:221], v[6:9]
	s_setprio 0
	s_setprio 1
	v_mfma_f32_16x16x32_bf16 v[62:65], v[168:171], v[188:191], v[62:65]
	v_mfma_f32_16x16x32_bf16 v[50:53], v[180:183], v[188:191], v[50:53]
	v_mfma_f32_16x16x32_bf16 v[46:49], v[168:171], v[196:199], v[46:49]
	v_mfma_f32_16x16x32_bf16 v[34:37], v[180:183], v[196:199], v[34:37]
	v_mfma_f32_16x16x32_bf16 v[30:33], v[168:171], v[204:207], v[30:33]
	v_mfma_f32_16x16x32_bf16 v[18:21], v[180:183], v[204:207], v[18:21]
	v_mfma_f32_16x16x32_bf16 v[14:17], v[168:171], v[214:217], v[14:17]
	v_mfma_f32_16x16x32_bf16 v[2:5], v[180:183], v[214:217], v[2:5]
	v_mfma_f32_16x16x32_bf16 v[62:65], v[172:175], v[192:195], v[62:65]
	v_mfma_f32_16x16x32_bf16 v[50:53], v[184:187], v[192:195], v[50:53]
	v_mfma_f32_16x16x32_bf16 v[46:49], v[172:175], v[200:203], v[46:49]
	v_mfma_f32_16x16x32_bf16 v[34:37], v[184:187], v[200:203], v[34:37]
	v_mfma_f32_16x16x32_bf16 v[30:33], v[172:175], v[210:213], v[30:33]
	v_mfma_f32_16x16x32_bf16 v[18:21], v[184:187], v[210:213], v[18:21]
	v_mfma_f32_16x16x32_bf16 v[14:17], v[172:175], v[218:221], v[14:17]
	v_mfma_f32_16x16x32_bf16 v[2:5], v[184:187], v[218:221], v[2:5]
	s_setprio 0
	s_barrier
	s_add_i32 s56, 0, 0x18000
	s_add_i32 s57, 0, 0x1c000
	v_add_u32_e32 v164, s56, v151
	v_add_u32_e32 v179, s57, v151
	ds_read_b128 v[146:149], v164
	ds_read_b128 v[156:159], v164 offset:1024
	ds_read_b128 v[160:163], v164 offset:2048
	ds_read_b128 v[164:167], v164 offset:3072
	ds_read_b128 v[168:171], v179
	ds_read_b128 v[172:175], v179 offset:1024
	ds_read_b128 v[180:183], v179 offset:2048
	ds_read_b128 v[184:187], v179 offset:3072
	s_add_u32 s28, s28, 0x40000
	s_addc_u32 s29, s29, 0
	s_mov_b32 m0, s39
	v_lshl_add_u64 v[226:227], s[28:29], 0, v[136:137]
	ds_read_b128 v[188:191], v155 offset:32768
	ds_read_b128 v[192:195], v155 offset:33792
	ds_read_b128 v[196:199], v155 offset:34816
	ds_read_b128 v[200:203], v155 offset:35840
	ds_read_b128 v[204:207], v155 offset:36864
	ds_read_b128 v[210:213], v155 offset:37888
	ds_read_b128 v[214:217], v155 offset:38912
	ds_read_b128 v[218:221], v155 offset:39936
	global_load_lds_dwordx4 v[226:227], off
	v_lshl_add_u64 v[226:227], s[28:29], 0, v[132:133]
	s_mov_b32 m0, s40
	s_nop 0
	global_load_lds_dwordx4 v[226:227], off
	s_waitcnt vmcnt(8)
	s_waitcnt lgkmcnt(0)
	s_barrier
	s_setprio 1
	v_mfma_f32_16x16x32_bf16 v[122:125], v[146:149], v[188:191], v[122:125]
	v_mfma_f32_16x16x32_bf16 v[114:117], v[160:163], v[188:191], v[114:117]
	v_mfma_f32_16x16x32_bf16 v[106:109], v[146:149], v[196:199], v[106:109]
	v_mfma_f32_16x16x32_bf16 v[98:101], v[160:163], v[196:199], v[98:101]
	v_mfma_f32_16x16x32_bf16 v[90:93], v[146:149], v[204:207], v[90:93]
	v_mfma_f32_16x16x32_bf16 v[82:85], v[160:163], v[204:207], v[82:85]
	v_mfma_f32_16x16x32_bf16 v[74:77], v[146:149], v[214:217], v[74:77]
	v_mfma_f32_16x16x32_bf16 v[70:73], v[160:163], v[214:217], v[70:73]
	v_mfma_f32_16x16x32_bf16 v[122:125], v[156:159], v[192:195], v[122:125]
	v_mfma_f32_16x16x32_bf16 v[114:117], v[164:167], v[192:195], v[114:117]
	v_mfma_f32_16x16x32_bf16 v[106:109], v[156:159], v[200:203], v[106:109]
	v_mfma_f32_16x16x32_bf16 v[98:101], v[164:167], v[200:203], v[98:101]
	v_mfma_f32_16x16x32_bf16 v[90:93], v[156:159], v[210:213], v[90:93]
	v_mfma_f32_16x16x32_bf16 v[82:85], v[164:167], v[210:213], v[82:85]
	v_mfma_f32_16x16x32_bf16 v[74:77], v[156:159], v[218:221], v[74:77]
	v_mfma_f32_16x16x32_bf16 v[70:73], v[164:167], v[218:221], v[70:73]
	s_setprio 0
	s_setprio 1
	v_mfma_f32_16x16x32_bf16 v[126:129], v[168:171], v[188:191], v[126:129]
	v_mfma_f32_16x16x32_bf16 v[118:121], v[180:183], v[188:191], v[118:121]
	v_mfma_f32_16x16x32_bf16 v[110:113], v[168:171], v[196:199], v[110:113]
	v_mfma_f32_16x16x32_bf16 v[102:105], v[180:183], v[196:199], v[102:105]
	v_mfma_f32_16x16x32_bf16 v[94:97], v[168:171], v[204:207], v[94:97]
	v_mfma_f32_16x16x32_bf16 v[86:89], v[180:183], v[204:207], v[86:89]
	v_mfma_f32_16x16x32_bf16 v[78:81], v[168:171], v[214:217], v[78:81]
	v_mfma_f32_16x16x32_bf16 v[66:69], v[180:183], v[214:217], v[66:69]
	v_mfma_f32_16x16x32_bf16 v[126:129], v[172:175], v[192:195], v[126:129]
	v_mfma_f32_16x16x32_bf16 v[118:121], v[184:187], v[192:195], v[118:121]
	v_mfma_f32_16x16x32_bf16 v[110:113], v[172:175], v[200:203], v[110:113]
	v_mfma_f32_16x16x32_bf16 v[102:105], v[184:187], v[200:203], v[102:105]
	v_mfma_f32_16x16x32_bf16 v[94:97], v[172:175], v[210:213], v[94:97]
	v_mfma_f32_16x16x32_bf16 v[86:89], v[184:187], v[210:213], v[86:89]
	v_mfma_f32_16x16x32_bf16 v[78:81], v[172:175], v[218:221], v[78:81]
	v_mfma_f32_16x16x32_bf16 v[66:69], v[184:187], v[218:221], v[66:69]
	s_setprio 0
	s_barrier
	s_add_i32 s28, s56, s35
	v_lshl_add_u64 v[176:177], v[176:177], 0, s[10:11]
	s_mov_b32 m0, s28
	ds_read_b128 v[188:191], v155 offset:49152
	ds_read_b128 v[192:195], v155 offset:50176
	ds_read_b128 v[196:199], v155 offset:51200
	ds_read_b128 v[200:203], v155 offset:52224
	ds_read_b128 v[204:207], v155 offset:53248
	ds_read_b128 v[210:213], v155 offset:54272
	ds_read_b128 v[214:217], v155 offset:55296
	ds_read_b128 v[218:221], v155 offset:56320
	global_load_lds_dwordx4 v[176:177], off
	s_add_i32 m0, s28, 0x2000
	s_add_u32 s26, s26, 0x40080
	v_lshl_add_u64 v[176:177], v[208:209], 0, s[10:11]
	s_addc_u32 s27, s27, 0
	s_add_i32 s28, s57, s35
	global_load_lds_dwordx4 v[176:177], off
	v_lshl_add_u64 v[176:177], s[26:27], 0, v[134:135]
	s_mov_b32 m0, s28
	s_nop 0
	global_load_lds_dwordx4 v[176:177], off
	v_lshl_add_u64 v[176:177], s[26:27], 0, v[130:131]
	s_add_i32 m0, s28, 0x2000
	s_nop 0
	global_load_lds_dwordx4 v[176:177], off
	v_lshl_add_u64 v[176:177], v[222:223], 0, s[10:11]
	s_mov_b32 m0, s42
	s_nop 0
	global_load_lds_dwordx4 v[176:177], off
	v_lshl_add_u64 v[176:177], v[224:225], 0, s[10:11]
	s_mov_b32 m0, s43
	s_nop 0
	global_load_lds_dwordx4 v[176:177], off
	s_waitcnt vmcnt(8)
	s_waitcnt lgkmcnt(0)
	s_barrier
	s_setprio 1
	s_waitcnt lgkmcnt(0)
	v_mfma_f32_16x16x32_bf16 v[58:61], v[146:149], v[188:191], v[58:61]
	v_mfma_f32_16x16x32_bf16 v[54:57], v[160:163], v[188:191], v[54:57]
	v_mfma_f32_16x16x32_bf16 v[42:45], v[146:149], v[196:199], v[42:45]
	v_mfma_f32_16x16x32_bf16 v[38:41], v[160:163], v[196:199], v[38:41]
	v_mfma_f32_16x16x32_bf16 v[26:29], v[146:149], v[204:207], v[26:29]
	v_mfma_f32_16x16x32_bf16 v[22:25], v[160:163], v[204:207], v[22:25]
	v_mfma_f32_16x16x32_bf16 v[10:13], v[146:149], v[214:217], v[10:13]
	v_mfma_f32_16x16x32_bf16 v[6:9], v[160:163], v[214:217], v[6:9]
	v_mfma_f32_16x16x32_bf16 v[58:61], v[156:159], v[192:195], v[58:61]
	v_mfma_f32_16x16x32_bf16 v[54:57], v[164:167], v[192:195], v[54:57]
	v_mfma_f32_16x16x32_bf16 v[42:45], v[156:159], v[200:203], v[42:45]
	v_mfma_f32_16x16x32_bf16 v[38:41], v[164:167], v[200:203], v[38:41]
	v_mfma_f32_16x16x32_bf16 v[26:29], v[156:159], v[210:213], v[26:29]
	v_mfma_f32_16x16x32_bf16 v[22:25], v[164:167], v[210:213], v[22:25]
	v_mfma_f32_16x16x32_bf16 v[10:13], v[156:159], v[218:221], v[10:13]
	v_mfma_f32_16x16x32_bf16 v[6:9], v[164:167], v[218:221], v[6:9]
	s_setprio 0
	s_setprio 1
	v_mfma_f32_16x16x32_bf16 v[62:65], v[168:171], v[188:191], v[62:65]
	v_mfma_f32_16x16x32_bf16 v[50:53], v[180:183], v[188:191], v[50:53]
	v_mfma_f32_16x16x32_bf16 v[46:49], v[168:171], v[196:199], v[46:49]
	v_mfma_f32_16x16x32_bf16 v[34:37], v[180:183], v[196:199], v[34:37]
	v_mfma_f32_16x16x32_bf16 v[30:33], v[168:171], v[204:207], v[30:33]
	v_mfma_f32_16x16x32_bf16 v[18:21], v[180:183], v[204:207], v[18:21]
	v_mfma_f32_16x16x32_bf16 v[14:17], v[168:171], v[214:217], v[14:17]
	v_mfma_f32_16x16x32_bf16 v[2:5], v[180:183], v[214:217], v[2:5]
	v_mfma_f32_16x16x32_bf16 v[62:65], v[172:175], v[192:195], v[62:65]
	v_mfma_f32_16x16x32_bf16 v[50:53], v[184:187], v[192:195], v[50:53]
	v_mfma_f32_16x16x32_bf16 v[46:49], v[172:175], v[200:203], v[46:49]
	v_mfma_f32_16x16x32_bf16 v[34:37], v[184:187], v[200:203], v[34:37]
	v_mfma_f32_16x16x32_bf16 v[30:33], v[172:175], v[210:213], v[30:33]
	v_mfma_f32_16x16x32_bf16 v[18:21], v[184:187], v[210:213], v[18:21]
	v_mfma_f32_16x16x32_bf16 v[14:17], v[172:175], v[218:221], v[14:17]
	v_mfma_f32_16x16x32_bf16 v[2:5], v[184:187], v[218:221], v[2:5]
	s_setprio 0
	s_barrier
	s_add_i32 s55, s55, 2
	s_add_u32 s24, s24, 0x100
	s_addc_u32 s25, s25, 0
	s_add_u32 s53, s53, 0x100
	s_addc_u32 s54, s54, 0
	s_cmp_gt_u32 s55, 13
	s_cbranch_scc0 .LBB0_1558
	s_and_b64 vcc, exec, s[12:13]
	s_cbranch_vccz .LBB0_1561
	s_barrier

.LBB0_1652:
	ds_read_b128 v[150:153], v161
	ds_read_b128 v[164:167], v161 offset:1024
	ds_read_b128 v[168:171], v161 offset:2048
	ds_read_b128 v[172:175], v161 offset:3072
	ds_read_b128 v[180:183], v162
	ds_read_b128 v[184:187], v162 offset:1024
	ds_read_b128 v[196:199], v162 offset:2048
	ds_read_b128 v[200:203], v162 offset:3072
	s_add_u32 s18, s16, 0xfff50080
	s_addc_u32 s19, s17, -1
	s_cmp_eq_u32 s41, 40
	s_cselect_b32 s21, s5, s19
	s_cselect_b32 s20, s4, s18
	s_cselect_b32 s19, s15, s40
	s_cselect_b32 s18, s14, s39
	v_lshl_add_u64 v[154:155], s[16:17], 0, v[142:143]
	s_add_i32 m0, s24, 0xc000
	ds_read_b128 v[204:207], v163
	ds_read_b128 v[210:213], v163 offset:1024
	ds_read_b128 v[214:217], v163 offset:2048
	ds_read_b128 v[218:221], v163 offset:3072
	ds_read_b128 v[222:225], v163 offset:4096
	ds_read_b128 v[226:229], v163 offset:5120
	ds_read_b128 v[230:233], v163 offset:6144
	ds_read_b128 v[234:237], v163 offset:7168
	global_load_lds_dwordx4 v[154:155], off
	v_lshl_add_u64 v[154:155], s[16:17], 0, v[144:145]
	s_add_i32 m0, s24, 0xe000
	s_nop 0
	global_load_lds_dwordx4 v[154:155], off
	s_waitcnt vmcnt(8)
	s_waitcnt lgkmcnt(0)
	s_barrier
	s_setprio 1
	v_mfma_f32_16x16x32_bf16 v[126:129], v[150:153], v[204:207], v[126:129]
	v_mfma_f32_16x16x32_bf16 v[122:125], v[168:171], v[204:207], v[122:125]
	v_mfma_f32_16x16x32_bf16 v[110:113], v[150:153], v[214:217], v[110:113]
	v_mfma_f32_16x16x32_bf16 v[106:109], v[168:171], v[214:217], v[106:109]
	v_mfma_f32_16x16x32_bf16 v[94:97], v[150:153], v[222:225], v[94:97]
	v_mfma_f32_16x16x32_bf16 v[90:93], v[168:171], v[222:225], v[90:93]
	v_mfma_f32_16x16x32_bf16 v[78:81], v[150:153], v[230:233], v[78:81]
	v_mfma_f32_16x16x32_bf16 v[74:77], v[168:171], v[230:233], v[74:77]
	v_mfma_f32_16x16x32_bf16 v[126:129], v[164:167], v[210:213], v[126:129]
	v_mfma_f32_16x16x32_bf16 v[122:125], v[172:175], v[210:213], v[122:125]
	v_mfma_f32_16x16x32_bf16 v[110:113], v[164:167], v[218:221], v[110:113]
	v_mfma_f32_16x16x32_bf16 v[106:109], v[172:175], v[218:221], v[106:109]
	v_mfma_f32_16x16x32_bf16 v[94:97], v[164:167], v[226:229], v[94:97]
	v_mfma_f32_16x16x32_bf16 v[90:93], v[172:175], v[226:229], v[90:93]
	v_mfma_f32_16x16x32_bf16 v[78:81], v[164:167], v[234:237], v[78:81]
	v_mfma_f32_16x16x32_bf16 v[74:77], v[172:175], v[234:237], v[74:77]
	s_setprio 0
	s_setprio 1
	v_mfma_f32_16x16x32_bf16 v[118:121], v[180:183], v[204:207], v[118:121]
	v_mfma_f32_16x16x32_bf16 v[114:117], v[196:199], v[204:207], v[114:117]
	v_mfma_f32_16x16x32_bf16 v[102:105], v[180:183], v[214:217], v[102:105]
	v_mfma_f32_16x16x32_bf16 v[98:101], v[196:199], v[214:217], v[98:101]
	v_mfma_f32_16x16x32_bf16 v[86:89], v[180:183], v[222:225], v[86:89]
	v_mfma_f32_16x16x32_bf16 v[82:85], v[196:199], v[222:225], v[82:85]
	v_mfma_f32_16x16x32_bf16 v[70:73], v[180:183], v[230:233], v[70:73]
	v_mfma_f32_16x16x32_bf16 v[66:69], v[196:199], v[230:233], v[66:69]
	v_mfma_f32_16x16x32_bf16 v[118:121], v[184:187], v[210:213], v[118:121]
	v_mfma_f32_16x16x32_bf16 v[114:117], v[200:203], v[210:213], v[114:117]
	v_mfma_f32_16x16x32_bf16 v[102:105], v[184:187], v[218:221], v[102:105]
	v_mfma_f32_16x16x32_bf16 v[98:101], v[200:203], v[218:221], v[98:101]
	v_mfma_f32_16x16x32_bf16 v[86:89], v[184:187], v[226:229], v[86:89]
	v_mfma_f32_16x16x32_bf16 v[82:85], v[200:203], v[226:229], v[82:85]
	v_mfma_f32_16x16x32_bf16 v[70:73], v[184:187], v[234:237], v[70:73]
	v_mfma_f32_16x16x32_bf16 v[66:69], v[200:203], v[234:237], v[66:69]
	s_setprio 0
	s_barrier
	s_add_i32 s42, s33, s23
	v_lshl_add_u64 v[154:155], s[18:19], 0, v[132:133]
	s_mov_b32 m0, s42
	ds_read_b128 v[204:207], v163 offset:16384
	ds_read_b128 v[210:213], v163 offset:17408
	ds_read_b128 v[214:217], v163 offset:18432
	ds_read_b128 v[218:221], v163 offset:19456
	ds_read_b128 v[222:225], v163 offset:20480
	ds_read_b128 v[226:229], v163 offset:21504
	ds_read_b128 v[230:233], v163 offset:22528
	ds_read_b128 v[234:237], v163 offset:23552
	global_load_lds_dwordx4 v[154:155], off
	s_add_i32 m0, s42, 0x2000
	s_add_u32 s42, s18, 0xb0000
	v_lshl_add_u64 v[176:177], s[18:19], 0, v[136:137]
	s_addc_u32 s43, s19, 0
	s_add_i32 s44, s34, s23
	global_load_lds_dwordx4 v[176:177], off
	v_lshl_add_u64 v[188:189], s[42:43], 0, v[132:133]
	s_mov_b32 m0, s44
	v_lshl_add_u64 v[208:209], s[20:21], 0, v[134:135]
	global_load_lds_dwordx4 v[188:189], off
	v_lshl_add_u64 v[188:189], s[42:43], 0, v[136:137]
	s_add_i32 m0, s44, 0x2000
	s_nop 0
	global_load_lds_dwordx4 v[188:189], off
	v_lshl_add_u64 v[188:189], s[20:21], 0, v[130:131]
	s_mov_b32 m0, s24
	s_nop 0
	global_load_lds_dwordx4 v[188:189], off
	s_mov_b32 m0, s25
	s_nop 0
	global_load_lds_dwordx4 v[208:209], off
	s_waitcnt vmcnt(8)
	s_waitcnt lgkmcnt(0)
	s_barrier
	s_setprio 1
	v_mfma_f32_16x16x32_bf16 v[62:65], v[150:153], v[204:207], v[62:65]
	v_mfma_f32_16x16x32_bf16 v[58:61], v[168:171], v[204:207], v[58:61]
	v_mfma_f32_16x16x32_bf16 v[46:49], v[150:153], v[214:217], v[46:49]
	v_mfma_f32_16x16x32_bf16 v[42:45], v[168:171], v[214:217], v[42:45]
	v_mfma_f32_16x16x32_bf16 v[30:33], v[150:153], v[222:225], v[30:33]
	v_mfma_f32_16x16x32_bf16 v[26:29], v[168:171], v[222:225], v[26:29]
	v_mfma_f32_16x16x32_bf16 v[14:17], v[150:153], v[230:233], v[14:17]
	v_mfma_f32_16x16x32_bf16 v[10:13], v[168:171], v[230:233], v[10:13]
	v_mfma_f32_16x16x32_bf16 v[62:65], v[164:167], v[210:213], v[62:65]
	v_mfma_f32_16x16x32_bf16 v[58:61], v[172:175], v[210:213], v[58:61]
	v_mfma_f32_16x16x32_bf16 v[46:49], v[164:167], v[218:221], v[46:49]
	v_mfma_f32_16x16x32_bf16 v[42:45], v[172:175], v[218:221], v[42:45]
	v_mfma_f32_16x16x32_bf16 v[30:33], v[164:167], v[226:229], v[30:33]
	v_mfma_f32_16x16x32_bf16 v[26:29], v[172:175], v[226:229], v[26:29]
	v_mfma_f32_16x16x32_bf16 v[14:17], v[164:167], v[234:237], v[14:17]
	v_mfma_f32_16x16x32_bf16 v[10:13], v[172:175], v[234:237], v[10:13]
	s_setprio 0
	s_setprio 1
	v_mfma_f32_16x16x32_bf16 v[54:57], v[180:183], v[204:207], v[54:57]
	v_mfma_f32_16x16x32_bf16 v[50:53], v[196:199], v[204:207], v[50:53]
	v_mfma_f32_16x16x32_bf16 v[38:41], v[180:183], v[214:217], v[38:41]
	v_mfma_f32_16x16x32_bf16 v[34:37], v[196:199], v[214:217], v[34:37]
	v_mfma_f32_16x16x32_bf16 v[22:25], v[180:183], v[222:225], v[22:25]
	v_mfma_f32_16x16x32_bf16 v[18:21], v[196:199], v[222:225], v[18:21]
	v_mfma_f32_16x16x32_bf16 v[6:9], v[180:183], v[230:233], v[6:9]
	v_mfma_f32_16x16x32_bf16 v[2:5], v[196:199], v[230:233], v[2:5]
	v_mfma_f32_16x16x32_bf16 v[54:57], v[184:187], v[210:213], v[54:57]
	v_mfma_f32_16x16x32_bf16 v[50:53], v[200:203], v[210:213], v[50:53]
	v_mfma_f32_16x16x32_bf16 v[38:41], v[184:187], v[218:221], v[38:41]
	v_mfma_f32_16x16x32_bf16 v[34:37], v[200:203], v[218:221], v[34:37]
	v_mfma_f32_16x16x32_bf16 v[22:25], v[184:187], v[226:229], v[22:25]
	v_mfma_f32_16x16x32_bf16 v[18:21], v[200:203], v[226:229], v[18:21]
	v_mfma_f32_16x16x32_bf16 v[6:9], v[184:187], v[234:237], v[6:9]
	v_mfma_f32_16x16x32_bf16 v[2:5], v[200:203], v[234:237], v[2:5]
	s_setprio 0
	s_barrier
	s_add_i32 s42, 0, 0x18000
	v_add_u32_e32 v139, s42, v159
	s_add_i32 s43, 0, 0x1c000
	ds_read_b128 v[150:153], v139
	ds_read_b128 v[164:167], v139 offset:1024
	ds_read_b128 v[168:171], v139 offset:2048
	ds_read_b128 v[172:175], v139 offset:3072
	v_add_u32_e32 v139, s43, v159
	ds_read_b128 v[180:183], v139
	ds_read_b128 v[184:187], v139 offset:1024
	ds_read_b128 v[196:199], v139 offset:2048
	ds_read_b128 v[200:203], v139 offset:3072
	s_add_u32 s20, s20, 0xb0000
	s_addc_u32 s21, s21, 0
	s_mov_b32 m0, s26
	v_lshl_add_u64 v[238:239], s[20:21], 0, v[130:131]
	ds_read_b128 v[204:207], v163 offset:32768
	ds_read_b128 v[210:213], v163 offset:33792
	ds_read_b128 v[214:217], v163 offset:34816
	ds_read_b128 v[218:221], v163 offset:35840
	ds_read_b128 v[222:225], v163 offset:36864
	ds_read_b128 v[226:229], v163 offset:37888
	ds_read_b128 v[230:233], v163 offset:38912
	ds_read_b128 v[234:237], v163 offset:39936
	global_load_lds_dwordx4 v[238:239], off
	v_lshl_add_u64 v[238:239], s[20:21], 0, v[134:135]
	s_mov_b32 m0, s27
	s_nop 0
	global_load_lds_dwordx4 v[238:239], off
	s_waitcnt vmcnt(8)
	s_waitcnt lgkmcnt(0)
	s_barrier
	s_setprio 1
	v_mfma_f32_16x16x32_bf16 v[126:129], v[150:153], v[204:207], v[126:129]
	v_mfma_f32_16x16x32_bf16 v[122:125], v[168:171], v[204:207], v[122:125]
	v_mfma_f32_16x16x32_bf16 v[110:113], v[150:153], v[214:217], v[110:113]
	v_mfma_f32_16x16x32_bf16 v[106:109], v[168:171], v[214:217], v[106:109]
	v_mfma_f32_16x16x32_bf16 v[94:97], v[150:153], v[222:225], v[94:97]
	v_mfma_f32_16x16x32_bf16 v[90:93], v[168:171], v[222:225], v[90:93]
	v_mfma_f32_16x16x32_bf16 v[78:81], v[150:153], v[230:233], v[78:81]
	v_mfma_f32_16x16x32_bf16 v[74:77], v[168:171], v[230:233], v[74:77]
	v_mfma_f32_16x16x32_bf16 v[126:129], v[164:167], v[210:213], v[126:129]
	v_mfma_f32_16x16x32_bf16 v[122:125], v[172:175], v[210:213], v[122:125]
	v_mfma_f32_16x16x32_bf16 v[110:113], v[164:167], v[218:221], v[110:113]
	v_mfma_f32_16x16x32_bf16 v[106:109], v[172:175], v[218:221], v[106:109]
	v_mfma_f32_16x16x32_bf16 v[94:97], v[164:167], v[226:229], v[94:97]
	v_mfma_f32_16x16x32_bf16 v[90:93], v[172:175], v[226:229], v[90:93]
	v_mfma_f32_16x16x32_bf16 v[78:81], v[164:167], v[234:237], v[78:81]
	v_mfma_f32_16x16x32_bf16 v[74:77], v[172:175], v[234:237], v[74:77]
	s_setprio 0
	s_setprio 1
	v_mfma_f32_16x16x32_bf16 v[118:121], v[180:183], v[204:207], v[118:121]
	v_mfma_f32_16x16x32_bf16 v[114:117], v[196:199], v[204:207], v[114:117]
	v_mfma_f32_16x16x32_bf16 v[102:105], v[180:183], v[214:217], v[102:105]
	v_mfma_f32_16x16x32_bf16 v[98:101], v[196:199], v[214:217], v[98:101]
	v_mfma_f32_16x16x32_bf16 v[86:89], v[180:183], v[222:225], v[86:89]
	v_mfma_f32_16x16x32_bf16 v[82:85], v[196:199], v[222:225], v[82:85]
	v_mfma_f32_16x16x32_bf16 v[70:73], v[180:183], v[230:233], v[70:73]
	v_mfma_f32_16x16x32_bf16 v[66:69], v[196:199], v[230:233], v[66:69]
	v_mfma_f32_16x16x32_bf16 v[118:121], v[184:187], v[210:213], v[118:121]
	v_mfma_f32_16x16x32_bf16 v[114:117], v[200:203], v[210:213], v[114:117]
	v_mfma_f32_16x16x32_bf16 v[102:105], v[184:187], v[218:221], v[102:105]
	v_mfma_f32_16x16x32_bf16 v[98:101], v[200:203], v[218:221], v[98:101]
	v_mfma_f32_16x16x32_bf16 v[86:89], v[184:187], v[226:229], v[86:89]
	v_mfma_f32_16x16x32_bf16 v[82:85], v[200:203], v[226:229], v[82:85]
	v_mfma_f32_16x16x32_bf16 v[70:73], v[184:187], v[234:237], v[70:73]
	v_mfma_f32_16x16x32_bf16 v[66:69], v[200:203], v[234:237], v[66:69]
	s_setprio 0
	s_barrier
	s_add_i32 s20, s42, s23
	v_lshl_add_u64 v[154:155], v[154:155], 0, s[10:11]
	s_mov_b32 m0, s20
	ds_read_b128 v[204:207], v163 offset:49152
	ds_read_b128 v[210:213], v163 offset:50176
	ds_read_b128 v[214:217], v163 offset:51200
	ds_read_b128 v[218:221], v163 offset:52224
	ds_read_b128 v[222:225], v163 offset:53248
	ds_read_b128 v[226:229], v163 offset:54272
	ds_read_b128 v[230:233], v163 offset:55296
	ds_read_b128 v[234:237], v163 offset:56320
	global_load_lds_dwordx4 v[154:155], off
	s_add_i32 m0, s20, 0x2000
	s_add_u32 s18, s18, 0xb0080
	v_lshl_add_u64 v[154:155], v[176:177], 0, s[10:11]
	s_addc_u32 s19, s19, 0
	s_add_i32 s20, s43, s23
	global_load_lds_dwordx4 v[154:155], off
	v_lshl_add_u64 v[154:155], s[18:19], 0, v[132:133]
	s_mov_b32 m0, s20
	s_nop 0
	global_load_lds_dwordx4 v[154:155], off
	v_lshl_add_u64 v[154:155], s[18:19], 0, v[136:137]
	s_add_i32 m0, s20, 0x2000
	s_nop 0
	global_load_lds_dwordx4 v[154:155], off
	v_lshl_add_u64 v[154:155], v[188:189], 0, s[10:11]
	s_mov_b32 m0, s29
	s_nop 0
	global_load_lds_dwordx4 v[154:155], off
	v_lshl_add_u64 v[154:155], v[208:209], 0, s[10:11]
	s_mov_b32 m0, s30
	s_nop 0
	global_load_lds_dwordx4 v[154:155], off
	s_waitcnt vmcnt(8)
	s_waitcnt lgkmcnt(0)
	s_barrier
	s_setprio 1
	s_waitcnt lgkmcnt(0)
	v_mfma_f32_16x16x32_bf16 v[62:65], v[150:153], v[204:207], v[62:65]
	v_mfma_f32_16x16x32_bf16 v[58:61], v[168:171], v[204:207], v[58:61]
	v_mfma_f32_16x16x32_bf16 v[46:49], v[150:153], v[214:217], v[46:49]
	v_mfma_f32_16x16x32_bf16 v[42:45], v[168:171], v[214:217], v[42:45]
	v_mfma_f32_16x16x32_bf16 v[30:33], v[150:153], v[222:225], v[30:33]
	v_mfma_f32_16x16x32_bf16 v[26:29], v[168:171], v[222:225], v[26:29]
	v_mfma_f32_16x16x32_bf16 v[14:17], v[150:153], v[230:233], v[14:17]
	v_mfma_f32_16x16x32_bf16 v[10:13], v[168:171], v[230:233], v[10:13]
	v_mfma_f32_16x16x32_bf16 v[62:65], v[164:167], v[210:213], v[62:65]
	v_mfma_f32_16x16x32_bf16 v[58:61], v[172:175], v[210:213], v[58:61]
	v_mfma_f32_16x16x32_bf16 v[46:49], v[164:167], v[218:221], v[46:49]
	v_mfma_f32_16x16x32_bf16 v[42:45], v[172:175], v[218:221], v[42:45]
	v_mfma_f32_16x16x32_bf16 v[30:33], v[164:167], v[226:229], v[30:33]
	v_mfma_f32_16x16x32_bf16 v[26:29], v[172:175], v[226:229], v[26:29]
	v_mfma_f32_16x16x32_bf16 v[14:17], v[164:167], v[234:237], v[14:17]
	v_mfma_f32_16x16x32_bf16 v[10:13], v[172:175], v[234:237], v[10:13]
	s_setprio 0
	s_setprio 1
	v_mfma_f32_16x16x32_bf16 v[54:57], v[180:183], v[204:207], v[54:57]
	v_mfma_f32_16x16x32_bf16 v[50:53], v[196:199], v[204:207], v[50:53]
	v_mfma_f32_16x16x32_bf16 v[38:41], v[180:183], v[214:217], v[38:41]
	v_mfma_f32_16x16x32_bf16 v[34:37], v[196:199], v[214:217], v[34:37]
	v_mfma_f32_16x16x32_bf16 v[22:25], v[180:183], v[222:225], v[22:25]
	v_mfma_f32_16x16x32_bf16 v[18:21], v[196:199], v[222:225], v[18:21]
	v_mfma_f32_16x16x32_bf16 v[6:9], v[180:183], v[230:233], v[6:9]
	v_mfma_f32_16x16x32_bf16 v[2:5], v[196:199], v[230:233], v[2:5]
	v_mfma_f32_16x16x32_bf16 v[54:57], v[184:187], v[210:213], v[54:57]
	v_mfma_f32_16x16x32_bf16 v[50:53], v[200:203], v[210:213], v[50:53]
	v_mfma_f32_16x16x32_bf16 v[38:41], v[184:187], v[218:221], v[38:41]
	v_mfma_f32_16x16x32_bf16 v[34:37], v[200:203], v[218:221], v[34:37]
	v_mfma_f32_16x16x32_bf16 v[22:25], v[184:187], v[226:229], v[22:25]
	v_mfma_f32_16x16x32_bf16 v[18:21], v[200:203], v[226:229], v[18:21]
	v_mfma_f32_16x16x32_bf16 v[6:9], v[184:187], v[234:237], v[6:9]
	v_mfma_f32_16x16x32_bf16 v[2:5], v[200:203], v[234:237], v[2:5]
	s_setprio 0
	s_barrier
	s_add_i32 s41, s41, 2
	s_add_u32 s16, s16, 0x100
	s_addc_u32 s17, s17, 0
	s_add_u32 s39, s39, 0x100
	s_addc_u32 s40, s40, 0
	s_cmp_gt_u32 s41, 41
	s_cbranch_scc0 .LBB0_1652
	s_and_b64 vcc, exec, s[12:13]
	s_cbranch_vccz .LBB0_1655
	s_barrier

.LBB0_1682:
	v_add_u32_e32 v164, s42, v150
	v_add_u32_e32 v181, s43, v150
	s_add_u32 s26, s22, s24
	ds_read_b128 v[152:155], v164
	ds_read_b128 v[156:159], v164 offset:1024
	ds_read_b128 v[160:163], v164 offset:2048
	ds_read_b128 v[164:167], v164 offset:3072
	ds_read_b128 v[168:171], v181
	ds_read_b128 v[172:175], v181 offset:1024
	ds_read_b128 v[176:179], v181 offset:2048
	ds_read_b128 v[182:185], v181 offset:3072
	s_addc_u32 s27, s23, s25
	s_add_u32 s26, s26, 0x100
	s_addc_u32 s27, s27, 0
	s_add_u32 s55, s19, s24
	s_addc_u32 s56, s49, s25
	s_cmpk_eq_i32 s24, 0x1500
	s_cselect_b32 s29, s7, s27
	s_cselect_b32 s28, s6, s26
	s_cselect_b32 s27, s21, s56
	s_cselect_b32 s26, s20, s55
	v_lshl_add_u64 v[208:209], v[146:147], 0, s[24:25]
	s_add_i32 m0, s35, 0xc000
	ds_read_b128 v[186:189], v151
	ds_read_b128 v[196:199], v151 offset:1024
	ds_read_b128 v[200:203], v151 offset:2048
	ds_read_b128 v[204:207], v151 offset:3072
	ds_read_b128 v[210:213], v151 offset:4096
	ds_read_b128 v[214:217], v151 offset:5120
	ds_read_b128 v[218:221], v151 offset:6144
	ds_read_b128 v[222:225], v151 offset:7168
	global_load_lds_dwordx4 v[208:209], off
	v_lshl_add_u64 v[208:209], v[148:149], 0, s[24:25]
	s_add_i32 m0, s35, 0xe000
	s_nop 0
	global_load_lds_dwordx4 v[208:209], off
	s_waitcnt vmcnt(8)
	s_waitcnt lgkmcnt(0)
	s_barrier
	s_setprio 1
	s_waitcnt lgkmcnt(0)
	v_mfma_f32_16x16x32_bf16 v[142:145], v[152:155], v[186:189], v[142:145]
	v_mfma_f32_16x16x32_bf16 v[138:141], v[160:163], v[186:189], v[138:141]
	v_mfma_f32_16x16x32_bf16 v[126:129], v[152:155], v[200:203], v[126:129]
	v_mfma_f32_16x16x32_bf16 v[122:125], v[160:163], v[200:203], v[122:125]
	v_mfma_f32_16x16x32_bf16 v[110:113], v[152:155], v[210:213], v[110:113]
	v_mfma_f32_16x16x32_bf16 v[106:109], v[160:163], v[210:213], v[106:109]
	v_mfma_f32_16x16x32_bf16 v[94:97], v[152:155], v[218:221], v[94:97]
	v_mfma_f32_16x16x32_bf16 v[90:93], v[160:163], v[218:221], v[90:93]
	v_mfma_f32_16x16x32_bf16 v[142:145], v[156:159], v[196:199], v[142:145]
	v_mfma_f32_16x16x32_bf16 v[138:141], v[164:167], v[196:199], v[138:141]
	v_mfma_f32_16x16x32_bf16 v[126:129], v[156:159], v[204:207], v[126:129]
	v_mfma_f32_16x16x32_bf16 v[122:125], v[164:167], v[204:207], v[122:125]
	v_mfma_f32_16x16x32_bf16 v[110:113], v[156:159], v[214:217], v[110:113]
	v_mfma_f32_16x16x32_bf16 v[106:109], v[164:167], v[214:217], v[106:109]
	v_mfma_f32_16x16x32_bf16 v[94:97], v[156:159], v[222:225], v[94:97]
	v_mfma_f32_16x16x32_bf16 v[90:93], v[164:167], v[222:225], v[90:93]
	s_setprio 0
	s_setprio 1
	v_mfma_f32_16x16x32_bf16 v[134:137], v[168:171], v[186:189], v[134:137]
	v_mfma_f32_16x16x32_bf16 v[130:133], v[176:179], v[186:189], v[130:133]
	v_mfma_f32_16x16x32_bf16 v[118:121], v[168:171], v[200:203], v[118:121]
	v_mfma_f32_16x16x32_bf16 v[114:117], v[176:179], v[200:203], v[114:117]
	v_mfma_f32_16x16x32_bf16 v[102:105], v[168:171], v[210:213], v[102:105]
	v_mfma_f32_16x16x32_bf16 v[98:101], v[176:179], v[210:213], v[98:101]
	v_mfma_f32_16x16x32_bf16 v[86:89], v[168:171], v[218:221], v[86:89]
	v_mfma_f32_16x16x32_bf16 v[82:85], v[176:179], v[218:221], v[82:85]
	v_mfma_f32_16x16x32_bf16 v[134:137], v[172:175], v[196:199], v[134:137]
	v_mfma_f32_16x16x32_bf16 v[130:133], v[182:185], v[196:199], v[130:133]
	v_mfma_f32_16x16x32_bf16 v[118:121], v[172:175], v[204:207], v[118:121]
	v_mfma_f32_16x16x32_bf16 v[114:117], v[182:185], v[204:207], v[114:117]
	v_mfma_f32_16x16x32_bf16 v[102:105], v[172:175], v[214:217], v[102:105]
	v_mfma_f32_16x16x32_bf16 v[98:101], v[182:185], v[214:217], v[98:101]
	v_mfma_f32_16x16x32_bf16 v[86:89], v[172:175], v[222:225], v[86:89]
	v_mfma_f32_16x16x32_bf16 v[82:85], v[182:185], v[222:225], v[82:85]
	s_setprio 0
	s_barrier
	s_add_i32 s55, s42, s33
	v_lshl_add_u64 v[208:209], s[26:27], 0, v[4:5]
	s_mov_b32 m0, s55
	ds_read_b128 v[186:189], v151 offset:16384
	ds_read_b128 v[196:199], v151 offset:17408
	ds_read_b128 v[200:203], v151 offset:18432
	ds_read_b128 v[204:207], v151 offset:19456
	ds_read_b128 v[210:213], v151 offset:20480
	ds_read_b128 v[214:217], v151 offset:21504
	ds_read_b128 v[218:221], v151 offset:22528
	ds_read_b128 v[222:225], v151 offset:23552
	global_load_lds_dwordx4 v[208:209], off
	s_add_i32 m0, s55, 0x2000
	s_add_u32 s56, s26, 0xb0000
	v_lshl_add_u64 v[226:227], s[26:27], 0, v[8:9]
	s_addc_u32 s57, s27, 0
	s_add_i32 s55, s43, s33
	global_load_lds_dwordx4 v[226:227], off
	v_lshl_add_u64 v[228:229], s[56:57], 0, v[4:5]
	s_mov_b32 m0, s55
	v_lshl_add_u64 v[230:231], s[28:29], 0, v[6:7]
	global_load_lds_dwordx4 v[228:229], off
	v_lshl_add_u64 v[228:229], s[56:57], 0, v[8:9]
	s_add_i32 m0, s55, 0x2000
	s_nop 0
	global_load_lds_dwordx4 v[228:229], off
	v_lshl_add_u64 v[228:229], s[28:29], 0, v[2:3]
	s_mov_b32 m0, s35
	s_nop 0
	global_load_lds_dwordx4 v[228:229], off
	s_mov_b32 m0, s36
	s_nop 0
	global_load_lds_dwordx4 v[230:231], off
	s_waitcnt vmcnt(8)
	s_waitcnt lgkmcnt(0)
	s_barrier
	s_setprio 1
	v_mfma_f32_16x16x32_bf16 v[78:81], v[152:155], v[186:189], v[78:81]
	v_mfma_f32_16x16x32_bf16 v[74:77], v[160:163], v[186:189], v[74:77]
	v_mfma_f32_16x16x32_bf16 v[62:65], v[152:155], v[200:203], v[62:65]
	v_mfma_f32_16x16x32_bf16 v[58:61], v[160:163], v[200:203], v[58:61]
	v_mfma_f32_16x16x32_bf16 v[46:49], v[152:155], v[210:213], v[46:49]
	v_mfma_f32_16x16x32_bf16 v[42:45], v[160:163], v[210:213], v[42:45]
	v_mfma_f32_16x16x32_bf16 v[30:33], v[152:155], v[218:221], v[30:33]
	v_mfma_f32_16x16x32_bf16 v[26:29], v[160:163], v[218:221], v[26:29]
	v_mfma_f32_16x16x32_bf16 v[78:81], v[156:159], v[196:199], v[78:81]
	v_mfma_f32_16x16x32_bf16 v[74:77], v[164:167], v[196:199], v[74:77]
	v_mfma_f32_16x16x32_bf16 v[62:65], v[156:159], v[204:207], v[62:65]
	v_mfma_f32_16x16x32_bf16 v[58:61], v[164:167], v[204:207], v[58:61]
	v_mfma_f32_16x16x32_bf16 v[46:49], v[156:159], v[214:217], v[46:49]
	v_mfma_f32_16x16x32_bf16 v[42:45], v[164:167], v[214:217], v[42:45]
	v_mfma_f32_16x16x32_bf16 v[30:33], v[156:159], v[222:225], v[30:33]
	v_mfma_f32_16x16x32_bf16 v[26:29], v[164:167], v[222:225], v[26:29]
	s_setprio 0
	s_setprio 1
	v_mfma_f32_16x16x32_bf16 v[70:73], v[168:171], v[186:189], v[70:73]
	v_mfma_f32_16x16x32_bf16 v[66:69], v[176:179], v[186:189], v[66:69]
	v_mfma_f32_16x16x32_bf16 v[54:57], v[168:171], v[200:203], v[54:57]
	v_mfma_f32_16x16x32_bf16 v[50:53], v[176:179], v[200:203], v[50:53]
	v_mfma_f32_16x16x32_bf16 v[38:41], v[168:171], v[210:213], v[38:41]
	v_mfma_f32_16x16x32_bf16 v[34:37], v[176:179], v[210:213], v[34:37]
	v_mfma_f32_16x16x32_bf16 v[22:25], v[168:171], v[218:221], v[22:25]
	v_mfma_f32_16x16x32_bf16 v[18:21], v[176:179], v[218:221], v[18:21]
	v_mfma_f32_16x16x32_bf16 v[70:73], v[172:175], v[196:199], v[70:73]
	v_mfma_f32_16x16x32_bf16 v[66:69], v[182:185], v[196:199], v[66:69]
	v_mfma_f32_16x16x32_bf16 v[54:57], v[172:175], v[204:207], v[54:57]
	v_mfma_f32_16x16x32_bf16 v[50:53], v[182:185], v[204:207], v[50:53]
	v_mfma_f32_16x16x32_bf16 v[38:41], v[172:175], v[214:217], v[38:41]
	v_mfma_f32_16x16x32_bf16 v[34:37], v[182:185], v[214:217], v[34:37]
	v_mfma_f32_16x16x32_bf16 v[22:25], v[172:175], v[222:225], v[22:25]
	v_mfma_f32_16x16x32_bf16 v[18:21], v[182:185], v[222:225], v[18:21]
	s_setprio 0
	s_barrier
	s_add_i32 s55, 0, 0x18000
	s_add_i32 s56, 0, 0x1c000
	v_add_u32_e32 v164, s55, v150
	v_add_u32_e32 v181, s56, v150
	ds_read_b128 v[152:155], v164
	ds_read_b128 v[156:159], v164 offset:1024
	ds_read_b128 v[160:163], v164 offset:2048
	ds_read_b128 v[164:167], v164 offset:3072
	ds_read_b128 v[168:171], v181
	ds_read_b128 v[172:175], v181 offset:1024
	ds_read_b128 v[176:179], v181 offset:2048
	ds_read_b128 v[182:185], v181 offset:3072
	s_add_u32 s28, s28, 0xb0000
	s_addc_u32 s29, s29, 0
	s_mov_b32 m0, s37
	v_lshl_add_u64 v[232:233], s[28:29], 0, v[2:3]
	ds_read_b128 v[186:189], v151 offset:32768
	ds_read_b128 v[196:199], v151 offset:33792
	ds_read_b128 v[200:203], v151 offset:34816
	ds_read_b128 v[204:207], v151 offset:35840
	ds_read_b128 v[210:213], v151 offset:36864
	ds_read_b128 v[214:217], v151 offset:37888
	ds_read_b128 v[218:221], v151 offset:38912
	ds_read_b128 v[222:225], v151 offset:39936
	global_load_lds_dwordx4 v[232:233], off
	v_lshl_add_u64 v[232:233], s[28:29], 0, v[6:7]
	s_mov_b32 m0, s38
	s_nop 0
	global_load_lds_dwordx4 v[232:233], off
	s_waitcnt vmcnt(8)
	s_waitcnt lgkmcnt(0)
	s_barrier
	s_setprio 1
	v_mfma_f32_16x16x32_bf16 v[142:145], v[152:155], v[186:189], v[142:145]
	v_mfma_f32_16x16x32_bf16 v[138:141], v[160:163], v[186:189], v[138:141]
	v_mfma_f32_16x16x32_bf16 v[126:129], v[152:155], v[200:203], v[126:129]
	v_mfma_f32_16x16x32_bf16 v[122:125], v[160:163], v[200:203], v[122:125]
	v_mfma_f32_16x16x32_bf16 v[110:113], v[152:155], v[210:213], v[110:113]
	v_mfma_f32_16x16x32_bf16 v[106:109], v[160:163], v[210:213], v[106:109]
	v_mfma_f32_16x16x32_bf16 v[94:97], v[152:155], v[218:221], v[94:97]
	v_mfma_f32_16x16x32_bf16 v[90:93], v[160:163], v[218:221], v[90:93]
	v_mfma_f32_16x16x32_bf16 v[142:145], v[156:159], v[196:199], v[142:145]
	v_mfma_f32_16x16x32_bf16 v[138:141], v[164:167], v[196:199], v[138:141]
	v_mfma_f32_16x16x32_bf16 v[126:129], v[156:159], v[204:207], v[126:129]
	v_mfma_f32_16x16x32_bf16 v[122:125], v[164:167], v[204:207], v[122:125]
	v_mfma_f32_16x16x32_bf16 v[110:113], v[156:159], v[214:217], v[110:113]
	v_mfma_f32_16x16x32_bf16 v[106:109], v[164:167], v[214:217], v[106:109]
	v_mfma_f32_16x16x32_bf16 v[94:97], v[156:159], v[222:225], v[94:97]
	v_mfma_f32_16x16x32_bf16 v[90:93], v[164:167], v[222:225], v[90:93]
	s_setprio 0
	s_setprio 1
	v_mfma_f32_16x16x32_bf16 v[134:137], v[168:171], v[186:189], v[134:137]
	v_mfma_f32_16x16x32_bf16 v[130:133], v[176:179], v[186:189], v[130:133]
	v_mfma_f32_16x16x32_bf16 v[118:121], v[168:171], v[200:203], v[118:121]
	v_mfma_f32_16x16x32_bf16 v[114:117], v[176:179], v[200:203], v[114:117]
	v_mfma_f32_16x16x32_bf16 v[102:105], v[168:171], v[210:213], v[102:105]
	v_mfma_f32_16x16x32_bf16 v[98:101], v[176:179], v[210:213], v[98:101]
	v_mfma_f32_16x16x32_bf16 v[86:89], v[168:171], v[218:221], v[86:89]
	v_mfma_f32_16x16x32_bf16 v[82:85], v[176:179], v[218:221], v[82:85]
	v_mfma_f32_16x16x32_bf16 v[134:137], v[172:175], v[196:199], v[134:137]
	v_mfma_f32_16x16x32_bf16 v[130:133], v[182:185], v[196:199], v[130:133]
	v_mfma_f32_16x16x32_bf16 v[118:121], v[172:175], v[204:207], v[118:121]
	v_mfma_f32_16x16x32_bf16 v[114:117], v[182:185], v[204:207], v[114:117]
	v_mfma_f32_16x16x32_bf16 v[102:105], v[172:175], v[214:217], v[102:105]
	v_mfma_f32_16x16x32_bf16 v[98:101], v[182:185], v[214:217], v[98:101]
	v_mfma_f32_16x16x32_bf16 v[86:89], v[172:175], v[222:225], v[86:89]
	v_mfma_f32_16x16x32_bf16 v[82:85], v[182:185], v[222:225], v[82:85]
	s_setprio 0
	s_barrier
	s_add_i32 s28, s55, s33
	v_lshl_add_u64 v[208:209], v[208:209], 0, s[14:15]
	s_mov_b32 m0, s28
	ds_read_b128 v[186:189], v151 offset:49152
	ds_read_b128 v[196:199], v151 offset:50176
	ds_read_b128 v[200:203], v151 offset:51200
	ds_read_b128 v[204:207], v151 offset:52224
	ds_read_b128 v[210:213], v151 offset:53248
	ds_read_b128 v[214:217], v151 offset:54272
	ds_read_b128 v[218:221], v151 offset:55296
	ds_read_b128 v[222:225], v151 offset:56320
	global_load_lds_dwordx4 v[208:209], off
	s_add_i32 m0, s28, 0x2000
	s_add_u32 s26, s26, 0xb0080
	v_lshl_add_u64 v[208:209], v[226:227], 0, s[14:15]
	s_addc_u32 s27, s27, 0
	s_add_i32 s28, s56, s33
	global_load_lds_dwordx4 v[208:209], off
	v_lshl_add_u64 v[208:209], s[26:27], 0, v[4:5]
	s_mov_b32 m0, s28
	s_nop 0
	global_load_lds_dwordx4 v[208:209], off
	v_lshl_add_u64 v[208:209], s[26:27], 0, v[8:9]
	s_add_i32 m0, s28, 0x2000
	s_nop 0
	global_load_lds_dwordx4 v[208:209], off
	v_lshl_add_u64 v[208:209], v[228:229], 0, s[14:15]
	s_mov_b32 m0, s40
	s_nop 0
	global_load_lds_dwordx4 v[208:209], off
	v_lshl_add_u64 v[208:209], v[230:231], 0, s[14:15]
	s_mov_b32 m0, s41
	s_nop 0
	global_load_lds_dwordx4 v[208:209], off
	s_waitcnt vmcnt(8)
	s_waitcnt lgkmcnt(0)
	s_barrier
	s_setprio 1
	s_waitcnt lgkmcnt(0)
	v_mfma_f32_16x16x32_bf16 v[78:81], v[152:155], v[186:189], v[78:81]
	v_mfma_f32_16x16x32_bf16 v[74:77], v[160:163], v[186:189], v[74:77]
	v_mfma_f32_16x16x32_bf16 v[62:65], v[152:155], v[200:203], v[62:65]
	v_mfma_f32_16x16x32_bf16 v[58:61], v[160:163], v[200:203], v[58:61]
	v_mfma_f32_16x16x32_bf16 v[46:49], v[152:155], v[210:213], v[46:49]
	v_mfma_f32_16x16x32_bf16 v[42:45], v[160:163], v[210:213], v[42:45]
	v_mfma_f32_16x16x32_bf16 v[30:33], v[152:155], v[218:221], v[30:33]
	v_mfma_f32_16x16x32_bf16 v[26:29], v[160:163], v[218:221], v[26:29]
	v_mfma_f32_16x16x32_bf16 v[78:81], v[156:159], v[196:199], v[78:81]
	v_mfma_f32_16x16x32_bf16 v[74:77], v[164:167], v[196:199], v[74:77]
	v_mfma_f32_16x16x32_bf16 v[62:65], v[156:159], v[204:207], v[62:65]
	v_mfma_f32_16x16x32_bf16 v[58:61], v[164:167], v[204:207], v[58:61]
	v_mfma_f32_16x16x32_bf16 v[46:49], v[156:159], v[214:217], v[46:49]
	v_mfma_f32_16x16x32_bf16 v[42:45], v[164:167], v[214:217], v[42:45]
	v_mfma_f32_16x16x32_bf16 v[30:33], v[156:159], v[222:225], v[30:33]
	v_mfma_f32_16x16x32_bf16 v[26:29], v[164:167], v[222:225], v[26:29]
	s_setprio 0
	s_setprio 1
	v_mfma_f32_16x16x32_bf16 v[70:73], v[168:171], v[186:189], v[70:73]
	v_mfma_f32_16x16x32_bf16 v[66:69], v[176:179], v[186:189], v[66:69]
	v_mfma_f32_16x16x32_bf16 v[54:57], v[168:171], v[200:203], v[54:57]
	v_mfma_f32_16x16x32_bf16 v[50:53], v[176:179], v[200:203], v[50:53]
	v_mfma_f32_16x16x32_bf16 v[38:41], v[168:171], v[210:213], v[38:41]
	v_mfma_f32_16x16x32_bf16 v[34:37], v[176:179], v[210:213], v[34:37]
	v_mfma_f32_16x16x32_bf16 v[22:25], v[168:171], v[218:221], v[22:25]
	v_mfma_f32_16x16x32_bf16 v[18:21], v[176:179], v[218:221], v[18:21]
	v_mfma_f32_16x16x32_bf16 v[70:73], v[172:175], v[196:199], v[70:73]
	v_mfma_f32_16x16x32_bf16 v[66:69], v[182:185], v[196:199], v[66:69]
	v_mfma_f32_16x16x32_bf16 v[54:57], v[172:175], v[204:207], v[54:57]
	v_mfma_f32_16x16x32_bf16 v[50:53], v[182:185], v[204:207], v[50:53]
	v_mfma_f32_16x16x32_bf16 v[38:41], v[172:175], v[214:217], v[38:41]
	v_mfma_f32_16x16x32_bf16 v[34:37], v[182:185], v[214:217], v[34:37]
	v_mfma_f32_16x16x32_bf16 v[22:25], v[172:175], v[222:225], v[22:25]
	v_mfma_f32_16x16x32_bf16 v[18:21], v[182:185], v[222:225], v[18:21]
	s_setprio 0
	s_barrier
	s_add_i32 s54, s54, 2
	s_add_u32 s24, s24, 0x100
	s_addc_u32 s25, s25, 0
	s_cmp_gt_u32 s54, 41
	s_cbranch_scc0 .LBB0_1682
	s_and_b64 vcc, exec, s[16:17]
	s_cbranch_vccz .LBB0_1685
	s_barrier

.LBB0_1770:
	s_add_u32 s34, s20, s11
	s_addc_u32 s35, s21, 0
	s_add_u32 s28, s34, 0x100
	s_addc_u32 s29, s35, 0
	s_and_b64 s[26:27], s[24:25], exec
	s_cselect_b32 s29, s13, s29
	s_cselect_b32 s28, s12, s28
	s_add_u32 s11, s18, s11
	s_addc_u32 s26, s19, 0
	s_add_u32 s11, s11, 0x100
	s_addc_u32 s26, s26, 0
	s_and_b64 s[24:25], s[24:25], exec
	s_cselect_b32 s31, s15, s26
	s_cselect_b32 s30, s14, s11
	s_add_u32 s36, s34, 0xb0080
	ds_read_b128 v[150:153], v147
	ds_read_b128 v[154:157], v147 offset:1024
	ds_read_b128 v[158:161], v147 offset:2048
	ds_read_b128 v[162:165], v147 offset:3072
	ds_read_b128 v[166:169], v148
	ds_read_b128 v[170:173], v148 offset:1024
	ds_read_b128 v[174:177], v148 offset:2048
	ds_read_b128 v[178:181], v148 offset:3072
	s_addc_u32 s37, s35, 0
	s_add_i32 s66, s48, s33
	s_add_i32 s63, s66, 0x2000
	s_add_u32 s34, s30, 0xb0000
	s_addc_u32 s35, s31, 0
	s_add_i32 s65, s49, s33
	s_add_i32 s64, s65, 0x2000
	s_add_i32 s62, 0, 0x18000
	s_add_i32 s61, 0, 0x1c000
	s_add_u32 s26, s28, 0xb0000
	s_addc_u32 s27, s29, 0
	s_add_i32 s60, s62, s33
	s_add_i32 s11, s60, 0x2000
	s_add_u32 s24, s30, 0xb0080
	s_addc_u32 s25, s31, 0
	s_add_i32 s68, s61, s33
	s_add_i32 s67, s68, 0x2000
	s_mov_b32 m0, s54
	v_lshl_add_u64 v[142:143], s[36:37], 0, v[136:137]
	ds_read_b128 v[182:185], v149
	ds_read_b128 v[186:189], v149 offset:1024
	ds_read_b128 v[190:193], v149 offset:2048
	ds_read_b128 v[194:197], v149 offset:3072
	ds_read_b128 v[198:201], v149 offset:4096
	ds_read_b128 v[202:205], v149 offset:5120
	ds_read_b128 v[210:213], v149 offset:6144
	ds_read_b128 v[214:217], v149 offset:7168
	global_load_lds_dwordx4 v[142:143], off
	v_lshl_add_u64 v[142:143], s[36:37], 0, v[132:133]
	s_mov_b32 m0, s55
	s_nop 0
	global_load_lds_dwordx4 v[142:143], off
	s_waitcnt vmcnt(8)
	s_waitcnt lgkmcnt(0)
	s_barrier
	s_setprio 1
	v_mfma_f32_16x16x32_bf16 v[126:129], v[150:153], v[182:185], v[126:129]
	v_mfma_f32_16x16x32_bf16 v[122:125], v[158:161], v[182:185], v[122:125]
	v_mfma_f32_16x16x32_bf16 v[114:117], v[150:153], v[190:193], v[114:117]
	v_mfma_f32_16x16x32_bf16 v[106:109], v[158:161], v[190:193], v[106:109]
	v_mfma_f32_16x16x32_bf16 v[98:101], v[150:153], v[198:201], v[98:101]
	v_mfma_f32_16x16x32_bf16 v[90:93], v[158:161], v[198:201], v[90:93]
	v_mfma_f32_16x16x32_bf16 v[82:85], v[150:153], v[210:213], v[82:85]
	v_mfma_f32_16x16x32_bf16 v[74:77], v[158:161], v[210:213], v[74:77]
	v_mfma_f32_16x16x32_bf16 v[126:129], v[154:157], v[186:189], v[126:129]
	v_mfma_f32_16x16x32_bf16 v[122:125], v[162:165], v[186:189], v[122:125]
	v_mfma_f32_16x16x32_bf16 v[114:117], v[154:157], v[194:197], v[114:117]
	v_mfma_f32_16x16x32_bf16 v[106:109], v[162:165], v[194:197], v[106:109]
	v_mfma_f32_16x16x32_bf16 v[98:101], v[154:157], v[202:205], v[98:101]
	v_mfma_f32_16x16x32_bf16 v[90:93], v[162:165], v[202:205], v[90:93]
	v_mfma_f32_16x16x32_bf16 v[82:85], v[154:157], v[214:217], v[82:85]
	v_mfma_f32_16x16x32_bf16 v[74:77], v[162:165], v[214:217], v[74:77]
	s_setprio 0
	s_setprio 1
	v_mfma_f32_16x16x32_bf16 v[118:121], v[166:169], v[182:185], v[118:121]
	v_mfma_f32_16x16x32_bf16 v[110:113], v[174:177], v[182:185], v[110:113]
	v_mfma_f32_16x16x32_bf16 v[102:105], v[166:169], v[190:193], v[102:105]
	v_mfma_f32_16x16x32_bf16 v[94:97], v[174:177], v[190:193], v[94:97]
	v_mfma_f32_16x16x32_bf16 v[86:89], v[166:169], v[198:201], v[86:89]
	v_mfma_f32_16x16x32_bf16 v[78:81], v[174:177], v[198:201], v[78:81]
	v_mfma_f32_16x16x32_bf16 v[70:73], v[166:169], v[210:213], v[70:73]
	v_mfma_f32_16x16x32_bf16 v[66:69], v[174:177], v[210:213], v[66:69]
	v_mfma_f32_16x16x32_bf16 v[118:121], v[170:173], v[186:189], v[118:121]
	v_mfma_f32_16x16x32_bf16 v[110:113], v[178:181], v[186:189], v[110:113]
	v_mfma_f32_16x16x32_bf16 v[102:105], v[170:173], v[194:197], v[102:105]
	v_mfma_f32_16x16x32_bf16 v[94:97], v[178:181], v[194:197], v[94:97]
	v_mfma_f32_16x16x32_bf16 v[86:89], v[170:173], v[202:205], v[86:89]
	v_mfma_f32_16x16x32_bf16 v[78:81], v[178:181], v[202:205], v[78:81]
	v_mfma_f32_16x16x32_bf16 v[70:73], v[170:173], v[214:217], v[70:73]
	v_mfma_f32_16x16x32_bf16 v[66:69], v[178:181], v[214:217], v[66:69]
	s_setprio 0
	s_barrier
	s_mov_b32 m0, s66
	v_lshl_add_u64 v[142:143], s[30:31], 0, v[134:135]
	ds_read_b128 v[182:185], v149 offset:16384
	ds_read_b128 v[186:189], v149 offset:17408
	ds_read_b128 v[190:193], v149 offset:18432
	ds_read_b128 v[194:197], v149 offset:19456
	ds_read_b128 v[198:201], v149 offset:20480
	ds_read_b128 v[202:205], v149 offset:21504
	ds_read_b128 v[210:213], v149 offset:22528
	ds_read_b128 v[214:217], v149 offset:23552
	global_load_lds_dwordx4 v[142:143], off
	v_lshl_add_u64 v[206:207], s[30:31], 0, v[130:131]
	s_mov_b32 m0, s63
	v_lshl_add_u64 v[208:209], s[34:35], 0, v[134:135]
	global_load_lds_dwordx4 v[206:207], off
	s_mov_b32 m0, s65
	v_lshl_add_u64 v[218:219], s[28:29], 0, v[132:133]
	global_load_lds_dwordx4 v[208:209], off
	v_lshl_add_u64 v[208:209], s[34:35], 0, v[130:131]
	s_mov_b32 m0, s64
	s_nop 0
	global_load_lds_dwordx4 v[208:209], off
	v_lshl_add_u64 v[208:209], s[28:29], 0, v[136:137]
	s_mov_b32 m0, s17
	s_nop 0
	global_load_lds_dwordx4 v[208:209], off
	s_mov_b32 m0, s38
	s_nop 0
	global_load_lds_dwordx4 v[218:219], off
	s_waitcnt vmcnt(8)
	s_waitcnt lgkmcnt(0)
	s_barrier
	s_setprio 1
	s_waitcnt lgkmcnt(0)
	v_mfma_f32_16x16x32_bf16 v[62:65], v[150:153], v[182:185], v[62:65]
	v_mfma_f32_16x16x32_bf16 v[58:61], v[158:161], v[182:185], v[58:61]
	v_mfma_f32_16x16x32_bf16 v[50:53], v[150:153], v[190:193], v[50:53]
	v_mfma_f32_16x16x32_bf16 v[42:45], v[158:161], v[190:193], v[42:45]
	v_mfma_f32_16x16x32_bf16 v[34:37], v[150:153], v[198:201], v[34:37]
	v_mfma_f32_16x16x32_bf16 v[26:29], v[158:161], v[198:201], v[26:29]
	v_mfma_f32_16x16x32_bf16 v[18:21], v[150:153], v[210:213], v[18:21]
	v_mfma_f32_16x16x32_bf16 v[10:13], v[158:161], v[210:213], v[10:13]
	v_mfma_f32_16x16x32_bf16 v[62:65], v[154:157], v[186:189], v[62:65]
	v_mfma_f32_16x16x32_bf16 v[58:61], v[162:165], v[186:189], v[58:61]
	v_mfma_f32_16x16x32_bf16 v[50:53], v[154:157], v[194:197], v[50:53]
	v_mfma_f32_16x16x32_bf16 v[42:45], v[162:165], v[194:197], v[42:45]
	v_mfma_f32_16x16x32_bf16 v[34:37], v[154:157], v[202:205], v[34:37]
	v_mfma_f32_16x16x32_bf16 v[26:29], v[162:165], v[202:205], v[26:29]
	v_mfma_f32_16x16x32_bf16 v[18:21], v[154:157], v[214:217], v[18:21]
	v_mfma_f32_16x16x32_bf16 v[10:13], v[162:165], v[214:217], v[10:13]
	s_setprio 0
	s_setprio 1
	v_mfma_f32_16x16x32_bf16 v[54:57], v[166:169], v[182:185], v[54:57]
	v_mfma_f32_16x16x32_bf16 v[46:49], v[174:177], v[182:185], v[46:49]
	v_mfma_f32_16x16x32_bf16 v[38:41], v[166:169], v[190:193], v[38:41]
	v_mfma_f32_16x16x32_bf16 v[30:33], v[174:177], v[190:193], v[30:33]
	v_mfma_f32_16x16x32_bf16 v[22:25], v[166:169], v[198:201], v[22:25]
	v_mfma_f32_16x16x32_bf16 v[14:17], v[174:177], v[198:201], v[14:17]
	v_mfma_f32_16x16x32_bf16 v[6:9], v[166:169], v[210:213], v[6:9]
	v_mfma_f32_16x16x32_bf16 v[2:5], v[174:177], v[210:213], v[2:5]
	v_mfma_f32_16x16x32_bf16 v[54:57], v[170:173], v[186:189], v[54:57]
	v_mfma_f32_16x16x32_bf16 v[46:49], v[178:181], v[186:189], v[46:49]
	v_mfma_f32_16x16x32_bf16 v[38:41], v[170:173], v[194:197], v[38:41]
	v_mfma_f32_16x16x32_bf16 v[30:33], v[178:181], v[194:197], v[30:33]
	v_mfma_f32_16x16x32_bf16 v[22:25], v[170:173], v[202:205], v[22:25]
	v_mfma_f32_16x16x32_bf16 v[14:17], v[178:181], v[202:205], v[14:17]
	v_mfma_f32_16x16x32_bf16 v[6:9], v[170:173], v[214:217], v[6:9]
	v_mfma_f32_16x16x32_bf16 v[2:5], v[178:181], v[214:217], v[2:5]
	s_setprio 0
	s_barrier
	v_add_u32_e32 v139, s62, v145
	ds_read_b128 v[150:153], v139
	ds_read_b128 v[154:157], v139 offset:1024
	ds_read_b128 v[158:161], v139 offset:2048
	ds_read_b128 v[162:165], v139 offset:3072
	v_add_u32_e32 v139, s61, v145
	ds_read_b128 v[166:169], v139
	ds_read_b128 v[170:173], v139 offset:1024
	ds_read_b128 v[174:177], v139 offset:2048
	ds_read_b128 v[178:181], v139 offset:3072
	s_mov_b32 m0, s39
	v_lshl_add_u64 v[220:221], s[26:27], 0, v[136:137]
	ds_read_b128 v[182:185], v149 offset:32768
	ds_read_b128 v[186:189], v149 offset:33792
	ds_read_b128 v[190:193], v149 offset:34816
	ds_read_b128 v[194:197], v149 offset:35840
	ds_read_b128 v[198:201], v149 offset:36864
	ds_read_b128 v[202:205], v149 offset:37888
	ds_read_b128 v[210:213], v149 offset:38912
	ds_read_b128 v[214:217], v149 offset:39936
	global_load_lds_dwordx4 v[220:221], off
	v_lshl_add_u64 v[220:221], s[26:27], 0, v[132:133]
	s_mov_b32 m0, s40
	s_nop 0
	global_load_lds_dwordx4 v[220:221], off
	s_waitcnt vmcnt(8)
	s_waitcnt lgkmcnt(0)
	s_barrier
	s_setprio 1
	s_waitcnt lgkmcnt(0)
	v_mfma_f32_16x16x32_bf16 v[126:129], v[150:153], v[182:185], v[126:129]
	v_mfma_f32_16x16x32_bf16 v[122:125], v[158:161], v[182:185], v[122:125]
	v_mfma_f32_16x16x32_bf16 v[114:117], v[150:153], v[190:193], v[114:117]
	v_mfma_f32_16x16x32_bf16 v[106:109], v[158:161], v[190:193], v[106:109]
	v_mfma_f32_16x16x32_bf16 v[98:101], v[150:153], v[198:201], v[98:101]
	v_mfma_f32_16x16x32_bf16 v[90:93], v[158:161], v[198:201], v[90:93]
	v_mfma_f32_16x16x32_bf16 v[82:85], v[150:153], v[210:213], v[82:85]
	v_mfma_f32_16x16x32_bf16 v[74:77], v[158:161], v[210:213], v[74:77]
	v_mfma_f32_16x16x32_bf16 v[126:129], v[154:157], v[186:189], v[126:129]
	v_mfma_f32_16x16x32_bf16 v[122:125], v[162:165], v[186:189], v[122:125]
	v_mfma_f32_16x16x32_bf16 v[114:117], v[154:157], v[194:197], v[114:117]
	v_mfma_f32_16x16x32_bf16 v[106:109], v[162:165], v[194:197], v[106:109]
	v_mfma_f32_16x16x32_bf16 v[98:101], v[154:157], v[202:205], v[98:101]
	v_mfma_f32_16x16x32_bf16 v[90:93], v[162:165], v[202:205], v[90:93]
	v_mfma_f32_16x16x32_bf16 v[82:85], v[154:157], v[214:217], v[82:85]
	v_mfma_f32_16x16x32_bf16 v[74:77], v[162:165], v[214:217], v[74:77]
	s_setprio 0
	s_setprio 1
	v_mfma_f32_16x16x32_bf16 v[118:121], v[166:169], v[182:185], v[118:121]
	v_mfma_f32_16x16x32_bf16 v[110:113], v[174:177], v[182:185], v[110:113]
	v_mfma_f32_16x16x32_bf16 v[102:105], v[166:169], v[190:193], v[102:105]
	v_mfma_f32_16x16x32_bf16 v[94:97], v[174:177], v[190:193], v[94:97]
	v_mfma_f32_16x16x32_bf16 v[86:89], v[166:169], v[198:201], v[86:89]
	v_mfma_f32_16x16x32_bf16 v[78:81], v[174:177], v[198:201], v[78:81]
	v_mfma_f32_16x16x32_bf16 v[70:73], v[166:169], v[210:213], v[70:73]
	v_mfma_f32_16x16x32_bf16 v[66:69], v[174:177], v[210:213], v[66:69]
	v_mfma_f32_16x16x32_bf16 v[118:121], v[170:173], v[186:189], v[118:121]
	v_mfma_f32_16x16x32_bf16 v[110:113], v[178:181], v[186:189], v[110:113]
	v_mfma_f32_16x16x32_bf16 v[102:105], v[170:173], v[194:197], v[102:105]
	v_mfma_f32_16x16x32_bf16 v[94:97], v[178:181], v[194:197], v[94:97]
	v_mfma_f32_16x16x32_bf16 v[86:89], v[170:173], v[202:205], v[86:89]
	v_mfma_f32_16x16x32_bf16 v[78:81], v[178:181], v[202:205], v[78:81]
	v_mfma_f32_16x16x32_bf16 v[70:73], v[170:173], v[214:217], v[70:73]
	v_mfma_f32_16x16x32_bf16 v[66:69], v[178:181], v[214:217], v[66:69]
	s_setprio 0
	s_barrier
	s_mov_b32 m0, s60
	v_lshl_add_u64 v[142:143], v[142:143], 0, s[6:7]
	ds_read_b128 v[182:185], v149 offset:49152
	ds_read_b128 v[186:189], v149 offset:50176
	ds_read_b128 v[190:193], v149 offset:51200
	ds_read_b128 v[194:197], v149 offset:52224
	ds_read_b128 v[198:201], v149 offset:53248
	ds_read_b128 v[202:205], v149 offset:54272
	ds_read_b128 v[210:213], v149 offset:55296
	ds_read_b128 v[214:217], v149 offset:56320
	global_load_lds_dwordx4 v[142:143], off
	v_lshl_add_u64 v[142:143], v[206:207], 0, s[6:7]
	s_mov_b32 m0, s11
	s_nop 0
	global_load_lds_dwordx4 v[142:143], off
	v_lshl_add_u64 v[142:143], s[24:25], 0, v[134:135]
	s_mov_b32 m0, s68
	s_nop 0
	global_load_lds_dwordx4 v[142:143], off
	v_lshl_add_u64 v[142:143], s[24:25], 0, v[130:131]
	s_mov_b32 m0, s67
	s_nop 0
	global_load_lds_dwordx4 v[142:143], off
	v_lshl_add_u64 v[142:143], v[208:209], 0, s[6:7]
	s_mov_b32 m0, s44
	s_nop 0
	global_load_lds_dwordx4 v[142:143], off
	v_lshl_add_u64 v[142:143], v[218:219], 0, s[6:7]
	s_mov_b32 m0, s45
	s_nop 0
	global_load_lds_dwordx4 v[142:143], off
	s_waitcnt vmcnt(8)
	s_waitcnt lgkmcnt(0)
	s_barrier
	s_setprio 1
	s_waitcnt lgkmcnt(0)
	v_mfma_f32_16x16x32_bf16 v[62:65], v[150:153], v[182:185], v[62:65]
	v_mfma_f32_16x16x32_bf16 v[58:61], v[158:161], v[182:185], v[58:61]
	v_mfma_f32_16x16x32_bf16 v[50:53], v[150:153], v[190:193], v[50:53]
	v_mfma_f32_16x16x32_bf16 v[42:45], v[158:161], v[190:193], v[42:45]
	v_mfma_f32_16x16x32_bf16 v[34:37], v[150:153], v[198:201], v[34:37]
	v_mfma_f32_16x16x32_bf16 v[26:29], v[158:161], v[198:201], v[26:29]
	v_mfma_f32_16x16x32_bf16 v[18:21], v[150:153], v[210:213], v[18:21]
	v_mfma_f32_16x16x32_bf16 v[10:13], v[158:161], v[210:213], v[10:13]
	v_mfma_f32_16x16x32_bf16 v[62:65], v[154:157], v[186:189], v[62:65]
	v_mfma_f32_16x16x32_bf16 v[58:61], v[162:165], v[186:189], v[58:61]
	v_mfma_f32_16x16x32_bf16 v[50:53], v[154:157], v[194:197], v[50:53]
	v_mfma_f32_16x16x32_bf16 v[42:45], v[162:165], v[194:197], v[42:45]
	v_mfma_f32_16x16x32_bf16 v[34:37], v[154:157], v[202:205], v[34:37]
	v_mfma_f32_16x16x32_bf16 v[26:29], v[162:165], v[202:205], v[26:29]
	v_mfma_f32_16x16x32_bf16 v[18:21], v[154:157], v[214:217], v[18:21]
	v_mfma_f32_16x16x32_bf16 v[10:13], v[162:165], v[214:217], v[10:13]
	s_setprio 0
	s_setprio 1
	v_mfma_f32_16x16x32_bf16 v[54:57], v[166:169], v[182:185], v[54:57]
	v_mfma_f32_16x16x32_bf16 v[46:49], v[174:177], v[182:185], v[46:49]
	v_mfma_f32_16x16x32_bf16 v[38:41], v[166:169], v[190:193], v[38:41]
	v_mfma_f32_16x16x32_bf16 v[30:33], v[174:177], v[190:193], v[30:33]
	v_mfma_f32_16x16x32_bf16 v[22:25], v[166:169], v[198:201], v[22:25]
	v_mfma_f32_16x16x32_bf16 v[14:17], v[174:177], v[198:201], v[14:17]
	v_mfma_f32_16x16x32_bf16 v[6:9], v[166:169], v[210:213], v[6:9]
	v_mfma_f32_16x16x32_bf16 v[2:5], v[174:177], v[210:213], v[2:5]
	v_mfma_f32_16x16x32_bf16 v[54:57], v[170:173], v[186:189], v[54:57]
	v_mfma_f32_16x16x32_bf16 v[46:49], v[178:181], v[186:189], v[46:49]
	v_mfma_f32_16x16x32_bf16 v[38:41], v[170:173], v[194:197], v[38:41]
	v_mfma_f32_16x16x32_bf16 v[30:33], v[178:181], v[194:197], v[30:33]
	v_mfma_f32_16x16x32_bf16 v[22:25], v[170:173], v[202:205], v[22:25]
	v_mfma_f32_16x16x32_bf16 v[14:17], v[178:181], v[202:205], v[14:17]
	v_mfma_f32_16x16x32_bf16 v[6:9], v[170:173], v[214:217], v[6:9]
	v_mfma_f32_16x16x32_bf16 v[2:5], v[178:181], v[214:217], v[2:5]
	s_setprio 0
	s_barrier
	s_movk_i32 s11, 0x100
	s_andn2_b64 vcc, exec, s[22:23]
	s_mov_b64 s[24:25], -1
	s_mov_b64 s[22:23], 0
	s_cbranch_vccz .LBB0_1770
	s_and_b64 vcc, exec, s[8:9]
	s_cbranch_vccz .LBB0_1773
	s_barrier
